# attention re-written: 4 query groups x 2 key halves per workgroup (half the LDS reads per wave), LDS-DMA staging in a 3-buffer ring, lazily updated softmax reference, halves merged at item end
# baseline (speedup 1.0000x reference)
.LBB0_189:
	s_cmp_lt_i32 s88, 3
	s_cselect_b64 s[18:19], -1, 0
	s_and_b64 s[4:5], s[18:19], s[4:5]
	s_andn2_b64 vcc, exec, s[4:5]
	s_cbranch_vccnz .LBB0_426
	s_add_u32 s16, s34, 0x28c4000
	s_addc_u32 s17, s35, 0
	s_add_u32 s6, s34, 0x8a44000
	s_addc_u32 s7, s35, 0
	s_add_u32 s8, s0, 0x120
	s_addc_u32 s9, s1, 0
	s_cmpk_lt_i32 s2, 0x100
	s_cbranch_scc0 .LBB0_197
	s_load_dword s9, s[0:1], 0x120
	v_readfirstlane_b32 s42, v205
	v_and_b32_e32 v192, 15, v204
	v_bfe_u32 v193, v204, 4, 2
	v_lshrrev_b32_e32 v194, 8, v204
	v_bfe_u32 v195, v204, 6, 2
	v_bfe_u32 v196, v204, 1, 3
	v_xor_b32_e32 v197, v193, v196
	v_xor_b32_e32 v198, 4, v197
	v_lshlrev_b32_e32 v197, 4, v197
	v_lshlrev_b32_e32 v198, 4, v198
	v_lshlrev_b32_e32 v199, 14, v194
	v_lshl_add_u32 v199, v192, 7, v199
	v_add_u32_e32 v242, v199, v197
	v_add_u32_e32 v243, v199, v198
	v_lshlrev_b32_e32 v199, 13, v195
	v_lshl_add_u32 v199, v192, 7, v199
	v_add_u32_e32 v199, 0x8000, v199
	v_add_u32_e32 v244, v199, v197
	v_add_u32_e32 v245, v199, v198
	v_add_u32_e32 v246, 0x10000, v242
	v_add_u32_e32 v248, 0x10000, v244
	v_add_u32_e32 v247, 0x10000, v243
	v_add_u32_e32 v249, 0x10000, v245
	v_lshrrev_b32_e32 v199, 3, v204
	v_and_b32_e32 v200, 7, v204
	v_bfe_u32 v201, v204, 4, 3
	v_xor_b32_e32 v200, v200, v201
	v_lshlrev_b32_e32 v200, 4, v200
	v_lshl_add_u32 v238, v199, 11, v200
	v_add_u32_e32 v239, 0x20000, v238
	v_add_u32_e32 v240, 0x40000, v238
	v_add_u32_e32 v241, 0x60000, v238
	s_lshl_b32 s42, s42, 10
	v_and_b32_e32 v202, 0xff, v204
	v_mul_u32_u24_e32 v202, 0x800, v202
	s_mov_b32 s8, s2
	s_and_b32 s44, s8, 7
	s_lshl_b32 s44, s44, 5
	s_lshr_b32 s45, s8, 3
	s_add_i32 s44, s44, s45
	s_lshr_b32 s45, s44, 6
	s_and_b32 s44, s44, 63
	s_and_b32 s98, s44, 7
	s_lshl_b32 s45, s45, 3
	s_add_i32 s45, s45, s98
	s_lshl_b32 s14, s45, 8
	s_lshr_b32 s44, s44, 3
	s_lshl_b32 s15, s44, 8
	s_mul_i32 s44, s14, 0x800
	s_add_u32 s44, s44, 0x8a44000
	s_add_u32 s10, s34, s44
	s_addc_u32 s11, s35, 0
	s_mul_i32 s44, s15, 0x800
	s_add_u32 s44, s44, 0x0
	s_add_u32 s12, s34, s44
	s_addc_u32 s13, s35, 0
	s_waitcnt vmcnt(0) lgkmcnt(0)
	s_barrier
	s_add_u32 m0, s42, 0x0
	s_nop 0
	global_load_lds_dwordx4 v238, s[10:11]
	s_add_u32 m0, s42, 0x2000
	s_nop 0
	global_load_lds_dwordx4 v239, s[10:11]
	s_add_u32 m0, s42, 0x4000
	s_nop 0
	global_load_lds_dwordx4 v240, s[10:11]
	s_add_u32 m0, s42, 0x6000
	s_nop 0
	global_load_lds_dwordx4 v241, s[10:11]
	s_add_u32 m0, s42, 0x8000
	s_nop 0
	global_load_lds_dwordx4 v238, s[12:13]
	s_add_u32 m0, s42, 0xa000
	s_nop 0
	global_load_lds_dwordx4 v239, s[12:13]
	s_add_u32 m0, s42, 0xc000
	s_nop 0
	global_load_lds_dwordx4 v240, s[12:13]
	s_add_u32 m0, s42, 0xe000
	s_nop 0
	global_load_lds_dwordx4 v241, s[12:13]
	s_waitcnt vmcnt(0)

.Lgl_afterA_proj:
	s_add_u32 s28, s28, 0x80
	s_addc_u32 s29, s29, 0
	s_add_u32 s30, s30, 0x80
	s_addc_u32 s31, s31, 0
	s_cmp_eq_u32 s33, 7
	s_cselect_b32 s28, s22, s28
	s_cselect_b32 s29, s23, s29
	s_cselect_b32 s30, s24, s30
	s_cselect_b32 s31, s25, s31
	s_setprio 1
	ds_read_b128 v[206:209], v248
	ds_read_b128 v[210:213], v248 offset:2048
	ds_read_b128 v[214:217], v248 offset:4096
	ds_read_b128 v[218:221], v248 offset:6144
	ds_read_b128 v[128:131], v246
	ds_read_b128 v[132:135], v246 offset:2048
	ds_read_b128 v[136:139], v246 offset:4096
	ds_read_b128 v[140:143], v246 offset:6144
	ds_read_b128 v[144:147], v246 offset:8192
	ds_read_b128 v[148:151], v246 offset:10240
	ds_read_b128 v[152:155], v246 offset:12288
	ds_read_b128 v[156:159], v246 offset:14336
	v_mfma_f32_16x16x32_bf16 v[96:99], v[222:225], v[184:187], v[96:99]
	v_mfma_f32_16x16x32_bf16 v[100:103], v[226:229], v[184:187], v[100:103]
	v_mfma_f32_16x16x32_bf16 v[104:107], v[230:233], v[184:187], v[104:107]
	v_mfma_f32_16x16x32_bf16 v[108:111], v[234:237], v[184:187], v[108:111]
	v_mfma_f32_16x16x32_bf16 v[112:115], v[222:225], v[188:191], v[112:115]
	v_mfma_f32_16x16x32_bf16 v[116:119], v[226:229], v[188:191], v[116:119]
	v_mfma_f32_16x16x32_bf16 v[120:123], v[230:233], v[188:191], v[120:123]
	v_mfma_f32_16x16x32_bf16 v[124:127], v[234:237], v[188:191], v[124:127]
	s_waitcnt lgkmcnt(7)
	v_mfma_f32_16x16x32_bf16 v[0:3], v[206:209], v[128:131], v[0:3]
	v_mfma_f32_16x16x32_bf16 v[4:7], v[210:213], v[128:131], v[4:7]
	v_mfma_f32_16x16x32_bf16 v[8:11], v[214:217], v[128:131], v[8:11]
	v_mfma_f32_16x16x32_bf16 v[12:15], v[218:221], v[128:131], v[12:15]
	s_add_u32 m0, s42, 0x0
	s_nop 0
	global_load_lds_dwordx4 v238, s[28:29]
	s_add_u32 m0, s42, 0x2000
	s_nop 0
	global_load_lds_dwordx4 v239, s[28:29]
	ds_read_b128 v[222:225], v249
	ds_read_b128 v[226:229], v249 offset:2048
	s_waitcnt lgkmcnt(8)
	v_mfma_f32_16x16x32_bf16 v[16:19], v[206:209], v[132:135], v[16:19]
	v_mfma_f32_16x16x32_bf16 v[20:23], v[210:213], v[132:135], v[20:23]
	v_mfma_f32_16x16x32_bf16 v[24:27], v[214:217], v[132:135], v[24:27]
	v_mfma_f32_16x16x32_bf16 v[28:31], v[218:221], v[132:135], v[28:31]
	s_add_u32 m0, s42, 0x4000
	s_nop 0
	global_load_lds_dwordx4 v240, s[28:29]
	s_add_u32 m0, s42, 0x6000
	s_nop 0
	global_load_lds_dwordx4 v241, s[28:29]
	ds_read_b128 v[230:233], v249 offset:4096
	ds_read_b128 v[234:237], v249 offset:6144
	s_waitcnt lgkmcnt(9)
	v_mfma_f32_16x16x32_bf16 v[32:35], v[206:209], v[136:139], v[32:35]
	v_mfma_f32_16x16x32_bf16 v[36:39], v[210:213], v[136:139], v[36:39]
	v_mfma_f32_16x16x32_bf16 v[40:43], v[214:217], v[136:139], v[40:43]
	v_mfma_f32_16x16x32_bf16 v[44:47], v[218:221], v[136:139], v[44:47]
	s_add_u32 m0, s42, 0x8000
	s_nop 0
	global_load_lds_dwordx4 v238, s[30:31]
	s_add_u32 m0, s42, 0xa000
	s_nop 0
	global_load_lds_dwordx4 v239, s[30:31]
	ds_read_b128 v[160:163], v247
	ds_read_b128 v[164:167], v247 offset:2048
	s_waitcnt lgkmcnt(10)
	v_mfma_f32_16x16x32_bf16 v[48:51], v[206:209], v[140:143], v[48:51]
	v_mfma_f32_16x16x32_bf16 v[52:55], v[210:213], v[140:143], v[52:55]
	v_mfma_f32_16x16x32_bf16 v[56:59], v[214:217], v[140:143], v[56:59]
	v_mfma_f32_16x16x32_bf16 v[60:63], v[218:221], v[140:143], v[60:63]
	s_add_u32 m0, s42, 0xc000
	s_nop 0
	global_load_lds_dwordx4 v240, s[30:31]
	s_add_u32 m0, s42, 0xe000
	s_nop 0
	global_load_lds_dwordx4 v241, s[30:31]
	ds_read_b128 v[168:171], v247 offset:4096
	ds_read_b128 v[172:175], v247 offset:6144
	s_waitcnt lgkmcnt(11)
	v_mfma_f32_16x16x32_bf16 v[64:67], v[206:209], v[144:147], v[64:67]
	v_mfma_f32_16x16x32_bf16 v[68:71], v[210:213], v[144:147], v[68:71]
	v_mfma_f32_16x16x32_bf16 v[72:75], v[214:217], v[144:147], v[72:75]
	v_mfma_f32_16x16x32_bf16 v[76:79], v[218:221], v[144:147], v[76:79]
	ds_read_b128 v[176:179], v247 offset:8192
	ds_read_b128 v[180:183], v247 offset:10240
	s_waitcnt lgkmcnt(12)
	v_mfma_f32_16x16x32_bf16 v[80:83], v[206:209], v[148:151], v[80:83]
	v_mfma_f32_16x16x32_bf16 v[84:87], v[210:213], v[148:151], v[84:87]
	v_mfma_f32_16x16x32_bf16 v[88:91], v[214:217], v[148:151], v[88:91]
	v_mfma_f32_16x16x32_bf16 v[92:95], v[218:221], v[148:151], v[92:95]
	ds_read_b128 v[184:187], v247 offset:12288
	ds_read_b128 v[188:191], v247 offset:14336
	s_waitcnt lgkmcnt(13)
	v_mfma_f32_16x16x32_bf16 v[96:99], v[206:209], v[152:155], v[96:99]
	v_mfma_f32_16x16x32_bf16 v[100:103], v[210:213], v[152:155], v[100:103]
	v_mfma_f32_16x16x32_bf16 v[104:107], v[214:217], v[152:155], v[104:107]
	v_mfma_f32_16x16x32_bf16 v[108:111], v[218:221], v[152:155], v[108:111]
	s_waitcnt lgkmcnt(12)
	v_mfma_f32_16x16x32_bf16 v[112:115], v[206:209], v[156:159], v[112:115]
	v_mfma_f32_16x16x32_bf16 v[116:119], v[210:213], v[156:159], v[116:119]
	v_mfma_f32_16x16x32_bf16 v[120:123], v[214:217], v[156:159], v[120:123]
	v_mfma_f32_16x16x32_bf16 v[124:127], v[218:221], v[156:159], v[124:127]
	s_waitcnt lgkmcnt(7)
	v_mfma_f32_16x16x32_bf16 v[0:3], v[222:225], v[160:163], v[0:3]
	v_mfma_f32_16x16x32_bf16 v[4:7], v[226:229], v[160:163], v[4:7]
	v_mfma_f32_16x16x32_bf16 v[8:11], v[230:233], v[160:163], v[8:11]
	v_mfma_f32_16x16x32_bf16 v[12:15], v[234:237], v[160:163], v[12:15]
	s_waitcnt lgkmcnt(6)
	v_mfma_f32_16x16x32_bf16 v[16:19], v[222:225], v[164:167], v[16:19]
	v_mfma_f32_16x16x32_bf16 v[20:23], v[226:229], v[164:167], v[20:23]
	v_mfma_f32_16x16x32_bf16 v[24:27], v[230:233], v[164:167], v[24:27]
	v_mfma_f32_16x16x32_bf16 v[28:31], v[234:237], v[164:167], v[28:31]
	s_waitcnt lgkmcnt(5)
	v_mfma_f32_16x16x32_bf16 v[32:35], v[222:225], v[168:171], v[32:35]
	v_mfma_f32_16x16x32_bf16 v[36:39], v[226:229], v[168:171], v[36:39]
	v_mfma_f32_16x16x32_bf16 v[40:43], v[230:233], v[168:171], v[40:43]
	v_mfma_f32_16x16x32_bf16 v[44:47], v[234:237], v[168:171], v[44:47]
	s_waitcnt lgkmcnt(4)
	v_mfma_f32_16x16x32_bf16 v[48:51], v[222:225], v[172:175], v[48:51]
	v_mfma_f32_16x16x32_bf16 v[52:55], v[226:229], v[172:175], v[52:55]
	v_mfma_f32_16x16x32_bf16 v[56:59], v[230:233], v[172:175], v[56:59]
	v_mfma_f32_16x16x32_bf16 v[60:63], v[234:237], v[172:175], v[60:63]
	s_waitcnt lgkmcnt(3)
	v_mfma_f32_16x16x32_bf16 v[64:67], v[222:225], v[176:179], v[64:67]
	v_mfma_f32_16x16x32_bf16 v[68:71], v[226:229], v[176:179], v[68:71]
	v_mfma_f32_16x16x32_bf16 v[72:75], v[230:233], v[176:179], v[72:75]
	v_mfma_f32_16x16x32_bf16 v[76:79], v[234:237], v[176:179], v[76:79]
	s_waitcnt lgkmcnt(2)
	v_mfma_f32_16x16x32_bf16 v[80:83], v[222:225], v[180:183], v[80:83]
	v_mfma_f32_16x16x32_bf16 v[84:87], v[226:229], v[180:183], v[84:87]
	v_mfma_f32_16x16x32_bf16 v[88:91], v[230:233], v[180:183], v[88:91]
	v_mfma_f32_16x16x32_bf16 v[92:95], v[234:237], v[180:183], v[92:95]
	s_setprio 0
	s_waitcnt lgkmcnt(0)
	s_add_u32 s28, s28, 0x80
	s_addc_u32 s29, s29, 0
	s_add_u32 s30, s30, 0x80
	s_addc_u32 s31, s31, 0
	s_add_i32 s33, s33, 1
	s_cmp_lt_u32 s33, 8
	s_cbranch_scc1 .Lgl_ktop_proj
	v_mfma_f32_16x16x32_bf16 v[96:99], v[222:225], v[184:187], v[96:99]
	v_mfma_f32_16x16x32_bf16 v[100:103], v[226:229], v[184:187], v[100:103]
	v_mfma_f32_16x16x32_bf16 v[104:107], v[230:233], v[184:187], v[104:107]
	v_mfma_f32_16x16x32_bf16 v[108:111], v[234:237], v[184:187], v[108:111]
	v_mfma_f32_16x16x32_bf16 v[112:115], v[222:225], v[188:191], v[112:115]
	v_mfma_f32_16x16x32_bf16 v[116:119], v[226:229], v[188:191], v[116:119]
	v_mfma_f32_16x16x32_bf16 v[120:123], v[230:233], v[188:191], v[120:123]
	v_mfma_f32_16x16x32_bf16 v[124:127], v[234:237], v[188:191], v[124:127]
	s_and_b32 s98, s14, 0xffff
	s_mul_i32 s98, s98, 0x1040
	s_lshl_b32 s99, s15, 1
	s_add_u32 s98, s98, s99
	s_add_u32 s98, s98, 0x28c4000
	s_add_u32 s100, s34, s98
	s_addc_u32 s101, s35, 0
	v_and_b32_e32 v160, 15, v204
	v_lshrrev_b32_e32 v161, 8, v204
	v_lshl_add_u32 v160, v161, 7, v160
	v_mul_u32_u24_e32 v160, 0x1040, v160
	v_and_b32_e32 v161, 0xc0, v204
	v_lshl_add_u32 v160, v161, 1, v160
	v_bfe_u32 v161, v204, 4, 1
	v_lshl_add_u32 v160, v161, 5, v160
	v_bfe_u32 v161, v204, 5, 1
	v_lshl_add_u32 v160, v161, 4, v160
	s_nop 7
	s_nop 7
	v_cvt_pk_bf16_f32 v0, v0, v1
	v_cvt_pk_bf16_f32 v1, v2, v3
	v_cvt_pk_bf16_f32 v2, v4, v5
	v_cvt_pk_bf16_f32 v3, v6, v7
	v_cvt_pk_bf16_f32 v8, v8, v9
	v_cvt_pk_bf16_f32 v9, v10, v11
	v_cvt_pk_bf16_f32 v10, v12, v13
	v_cvt_pk_bf16_f32 v11, v14, v15
	s_nop 1
	v_permlane16_swap_b32_e32 v0, v2
	v_permlane16_swap_b32_e32 v1, v3
	v_permlane16_swap_b32_e32 v8, v10
	v_permlane16_swap_b32_e32 v9, v11
	global_store_dwordx4 v160, v[0:3], s[100:101] sc1
	global_store_dwordx4 v160, v[8:11], s[100:101] offset:64 sc1
	s_add_u32 s100, s100, 0x10400
	s_addc_u32 s101, s101, 0
	v_cvt_pk_bf16_f32 v16, v16, v17
	v_cvt_pk_bf16_f32 v17, v18, v19
	v_cvt_pk_bf16_f32 v18, v20, v21
	v_cvt_pk_bf16_f32 v19, v22, v23
	v_cvt_pk_bf16_f32 v24, v24, v25
	v_cvt_pk_bf16_f32 v25, v26, v27
	v_cvt_pk_bf16_f32 v26, v28, v29
	v_cvt_pk_bf16_f32 v27, v30, v31
	s_nop 1
	v_permlane16_swap_b32_e32 v16, v18
	v_permlane16_swap_b32_e32 v17, v19
	v_permlane16_swap_b32_e32 v24, v26
	v_permlane16_swap_b32_e32 v25, v27
	global_store_dwordx4 v160, v[16:19], s[100:101] sc1
	global_store_dwordx4 v160, v[24:27], s[100:101] offset:64 sc1
	s_add_u32 s100, s100, 0x10400
	s_addc_u32 s101, s101, 0
	v_cvt_pk_bf16_f32 v32, v32, v33
	v_cvt_pk_bf16_f32 v33, v34, v35
	v_cvt_pk_bf16_f32 v34, v36, v37
	v_cvt_pk_bf16_f32 v35, v38, v39
	v_cvt_pk_bf16_f32 v40, v40, v41
	v_cvt_pk_bf16_f32 v41, v42, v43
	v_cvt_pk_bf16_f32 v42, v44, v45
	v_cvt_pk_bf16_f32 v43, v46, v47
	s_nop 1
	v_permlane16_swap_b32_e32 v32, v34
	v_permlane16_swap_b32_e32 v33, v35
	v_permlane16_swap_b32_e32 v40, v42
	v_permlane16_swap_b32_e32 v41, v43
	global_store_dwordx4 v160, v[32:35], s[100:101] sc1
	global_store_dwordx4 v160, v[40:43], s[100:101] offset:64 sc1
	s_add_u32 s100, s100, 0x10400
	s_addc_u32 s101, s101, 0
	v_cvt_pk_bf16_f32 v48, v48, v49
	v_cvt_pk_bf16_f32 v49, v50, v51
	v_cvt_pk_bf16_f32 v50, v52, v53
	v_cvt_pk_bf16_f32 v51, v54, v55
	v_cvt_pk_bf16_f32 v56, v56, v57
	v_cvt_pk_bf16_f32 v57, v58, v59
	v_cvt_pk_bf16_f32 v58, v60, v61
	v_cvt_pk_bf16_f32 v59, v62, v63
	s_nop 1
	v_permlane16_swap_b32_e32 v48, v50
	v_permlane16_swap_b32_e32 v49, v51
	v_permlane16_swap_b32_e32 v56, v58
	v_permlane16_swap_b32_e32 v57, v59
	global_store_dwordx4 v160, v[48:51], s[100:101] sc1
	global_store_dwordx4 v160, v[56:59], s[100:101] offset:64 sc1
	s_add_u32 s100, s100, 0x10400
	s_addc_u32 s101, s101, 0
	v_cvt_pk_bf16_f32 v64, v64, v65
	v_cvt_pk_bf16_f32 v65, v66, v67
	v_cvt_pk_bf16_f32 v66, v68, v69
	v_cvt_pk_bf16_f32 v67, v70, v71
	v_cvt_pk_bf16_f32 v72, v72, v73
	v_cvt_pk_bf16_f32 v73, v74, v75
	v_cvt_pk_bf16_f32 v74, v76, v77
	v_cvt_pk_bf16_f32 v75, v78, v79
	s_nop 1
	v_permlane16_swap_b32_e32 v64, v66
	v_permlane16_swap_b32_e32 v65, v67
	v_permlane16_swap_b32_e32 v72, v74
	v_permlane16_swap_b32_e32 v73, v75
	global_store_dwordx4 v160, v[64:67], s[100:101] sc1
	global_store_dwordx4 v160, v[72:75], s[100:101] offset:64 sc1
	s_add_u32 s100, s100, 0x10400
	s_addc_u32 s101, s101, 0
	v_cvt_pk_bf16_f32 v80, v80, v81
	v_cvt_pk_bf16_f32 v81, v82, v83
	v_cvt_pk_bf16_f32 v82, v84, v85
	v_cvt_pk_bf16_f32 v83, v86, v87
	v_cvt_pk_bf16_f32 v88, v88, v89
	v_cvt_pk_bf16_f32 v89, v90, v91
	v_cvt_pk_bf16_f32 v90, v92, v93
	v_cvt_pk_bf16_f32 v91, v94, v95
	s_nop 1
	v_permlane16_swap_b32_e32 v80, v82
	v_permlane16_swap_b32_e32 v81, v83
	v_permlane16_swap_b32_e32 v88, v90
	v_permlane16_swap_b32_e32 v89, v91
	global_store_dwordx4 v160, v[80:83], s[100:101] sc1
	global_store_dwordx4 v160, v[88:91], s[100:101] offset:64 sc1
	s_add_u32 s100, s100, 0x10400
	s_addc_u32 s101, s101, 0
	v_cvt_pk_bf16_f32 v96, v96, v97
	v_cvt_pk_bf16_f32 v97, v98, v99
	v_cvt_pk_bf16_f32 v98, v100, v101
	v_cvt_pk_bf16_f32 v99, v102, v103
	v_cvt_pk_bf16_f32 v104, v104, v105
	v_cvt_pk_bf16_f32 v105, v106, v107
	v_cvt_pk_bf16_f32 v106, v108, v109
	v_cvt_pk_bf16_f32 v107, v110, v111
	s_nop 1
	v_permlane16_swap_b32_e32 v96, v98
	v_permlane16_swap_b32_e32 v97, v99
	v_permlane16_swap_b32_e32 v104, v106
	v_permlane16_swap_b32_e32 v105, v107
	global_store_dwordx4 v160, v[96:99], s[100:101] sc1
	global_store_dwordx4 v160, v[104:107], s[100:101] offset:64 sc1
	s_add_u32 s100, s100, 0x10400
	s_addc_u32 s101, s101, 0
	v_cvt_pk_bf16_f32 v112, v112, v113
	v_cvt_pk_bf16_f32 v113, v114, v115
	v_cvt_pk_bf16_f32 v114, v116, v117
	v_cvt_pk_bf16_f32 v115, v118, v119
	v_cvt_pk_bf16_f32 v120, v120, v121
	v_cvt_pk_bf16_f32 v121, v122, v123
	v_cvt_pk_bf16_f32 v122, v124, v125
	v_cvt_pk_bf16_f32 v123, v126, v127
	s_nop 1
	v_permlane16_swap_b32_e32 v112, v114
	v_permlane16_swap_b32_e32 v113, v115
	v_permlane16_swap_b32_e32 v120, v122
	v_permlane16_swap_b32_e32 v121, v123
	global_store_dwordx4 v160, v[112:115], s[100:101] sc1
	global_store_dwordx4 v160, v[120:123], s[100:101] offset:64 sc1
	s_and_b64 vcc, exec, s[26:27]
	s_mov_b32 s14, s20
	s_mov_b32 s15, s21
	s_mov_b64 s[10:11], s[22:23]
	s_mov_b64 s[12:13], s[24:25]
	s_mov_b32 s8, s43
	s_mov_b32 s99, 0
	s_cbranch_vccz .Lgl_tile_proj
	s_waitcnt vmcnt(0)
	s_barrier

.LBB0_910:
.LBB0_911:
	s_load_dword s15, s[0:1], 0x120
	v_readfirstlane_b32 s18, v205
	v_and_b32_e32 v160, 63, v204
	v_and_b32_e32 v161, 15, v204
	v_bfe_u32 v162, v204, 4, 2
	s_nop 1
	s_lshr_b32 s20, s18, 2
	s_and_b32 s21, s18, 3
	s_lshl_b32 s19, s18, 11
	s_lshl_b32 s18, s18, 10
	v_bfe_u32 v163, v204, 3, 3
	v_lshrrev_b32_e32 v164, 6, v204
	v_lshl_add_u32 v165, v164, 4, v163
	v_and_b32_e32 v166, 7, v204
	v_bfe_u32 v167, v204, 4, 2
	v_xor_b32_e32 v168, v166, v167
	v_lshlrev_b32_e32 v168, 4, v168
	v_lshl_add_u32 v176, v165, 10, v168
	v_xor_b32_e32 v168, 4, v167
	v_xor_b32_e32 v168, v166, v168
	v_lshlrev_b32_e32 v168, 4, v168
	v_add_u32_e32 v165, 8, v165
	v_lshl_add_u32 v177, v165, 10, v168
	v_bfe_u32 v165, v204, 2, 4
	v_lshl_add_u32 v165, v164, 4, v165
	v_and_b32_e32 v166, 3, v204
	v_bfe_u32 v167, v204, 5, 1
	v_lshlrev_b32_e32 v167, 1, v167
	v_xor_b32_e32 v166, v166, v167
	v_lshlrev_b32_e32 v166, 4, v166
	v_lshl_add_u32 v178, v165, 6, v166
	v_bfe_u32 v165, v204, 4, 2
	v_lshl_add_u32 v165, v164, 3, v165
	v_and_b32_e32 v166, 15, v204
	v_and_b32_e32 v167, 15, v165
	v_xor_b32_e32 v167, v166, v167
	v_lshlrev_b32_e32 v167, 4, v167
	v_mul_u32_u24_e32 v168, 0x4400, v165
	v_add_u32_e32 v179, v168, v167
	v_add_u32_e32 v165, 4, v165
	v_and_b32_e32 v167, 15, v165
	v_xor_b32_e32 v167, v166, v167
	v_lshlrev_b32_e32 v167, 4, v167
	v_mul_u32_u24_e32 v168, 0x4400, v165
	v_add_u32_e32 v180, v168, v167
	v_mov_b32_e32 v169, s20
	v_lshl_add_u32 v170, v169, 6, v161
	v_bfe_u32 v171, v161, 1, 3
	v_xor_b32_e32 v172, v162, v171
	v_lshlrev_b32_e32 v172, 4, v172
	v_lshl_add_u32 v181, v170, 7, v172
	v_or_b32_e32 v172, 4, v162
	v_xor_b32_e32 v172, v172, v171
	v_lshlrev_b32_e32 v172, 4, v172
	v_lshl_add_u32 v182, v170, 7, v172
	v_bfe_u32 v171, v161, 3, 1
	v_lshlrev_b32_e32 v171, 1, v171
	v_xor_b32_e32 v172, v162, v171
	v_lshlrev_b32_e32 v172, 4, v172
	v_lshl_add_u32 v183, v170, 6, v172
	v_add_u32_e32 v183, 0x4000, v183
	v_lshrrev_b32_e32 v171, 1, v162
	v_and_b32_e32 v173, 1, v162
	v_lshlrev_b32_e32 v173, 3, v173
	v_lshl_add_u32 v173, v161, 8, v173
	v_add_u32_e32 v173, 0x6000, v173
	v_lshlrev_b32_e32 v174, 3, v169
	v_add_u32_e32 v172, 0, v174
	v_add_u32_e32 v172, v172, v171
	v_xor_b32_e32 v172, v172, v161
	v_lshlrev_b32_e32 v172, 4, v172
	v_add_u32_e32 v184, v173, v172
	v_add_u32_e32 v172, 2, v174
	v_add_u32_e32 v172, v172, v171
	v_xor_b32_e32 v172, v172, v161
	v_lshlrev_b32_e32 v172, 4, v172
	v_add_u32_e32 v185, v173, v172
	v_add_u32_e32 v172, 4, v174
	v_add_u32_e32 v172, v172, v171
	v_xor_b32_e32 v172, v172, v161
	v_lshlrev_b32_e32 v172, 4, v172
	v_add_u32_e32 v186, v173, v172
	v_add_u32_e32 v172, 6, v174
	v_add_u32_e32 v172, v172, v171
	v_xor_b32_e32 v172, v172, v161
	v_lshlrev_b32_e32 v172, 4, v172
	v_add_u32_e32 v187, v173, v172
	v_add_u32_e32 v188, 0xa000, v181
	v_add_u32_e32 v189, 0xa000, v182
	v_add_u32_e32 v190, 0xa000, v183
	v_add_u32_e32 v191, 0xa000, v184
	v_add_u32_e32 v192, 0xa000, v185
	v_add_u32_e32 v193, 0xa000, v186
	v_add_u32_e32 v194, 0xa000, v187
	v_add_u32_e32 v195, 0x14000, v181
	v_add_u32_e32 v196, 0x14000, v182
	v_add_u32_e32 v197, 0x14000, v183
	v_add_u32_e32 v198, 0x14000, v184
	v_add_u32_e32 v199, 0x14000, v185
	v_add_u32_e32 v200, 0x14000, v186
	v_add_u32_e32 v201, 0x14000, v187
	v_mov_b32_e32 v169, s21
	v_lshl_add_u32 v170, v169, 5, v161
	v_mul_u32_u24_e32 v171, 0x600, v170
	v_lshl_add_u32 v202, v162, 4, v171
	v_add_u32_e32 v203, 0x6000, v202
	v_lshlrev_b32_e32 v171, 11, v170
	v_lshl_add_u32 v246, v162, 3, v171
	s_waitcnt lgkmcnt(0)
	s_mov_b32 s14, s2
	s_mov_b32 s36, 0
.Lat_item:
	s_cmpk_lt_i32 s14, 0x100
	s_cbranch_scc0 .Lat_prompt
	s_and_b32 s21, s14, 7
	s_bfe_u32 s22, s14, 0x10003
	s_lshr_b32 s23, s14, 4
	s_lshl_b32 s24, s22, 11
	s_lshl_b32 s23, s23, 7
	s_add_i32 s24, s24, s23
	s_add_i32 s24, s24, 0x1000
	s_mul_i32 s25, s22, 0x900
	s_add_i32 s25, s25, 0x1000
	s_mov_b32 s16, 18
	s_branch .Lat_dec
.Lat_prompt:
	s_sub_i32 s26, s14, 0x100
	s_and_b32 s21, s26, 7
	s_lshr_b32 s26, s26, 3
	s_lshr_b32 s22, s26, 1
	s_and_b32 s23, s26, 1
	s_lshl_b32 s24, s22, 8
	s_lshl_b32 s23, s23, 7
	s_add_i32 s24, s24, s23
	s_lshl_b32 s25, s22, 8
	s_mov_b32 s16, 2
.Lat_dec:
	s_lshl_b32 s26, s25, 10
	s_lshl_b32 s27, s21, 7
	s_add_u32 s26, s26, s27
	s_add_u32 s26, s26, 0xb644000
	s_add_u32 s4, s34, s26
	s_addc_u32 s5, s35, 0
	s_lshl_b32 s26, s25, 6
	s_add_u32 s26, s26, 0xcf84000
	s_add_u32 s6, s34, s26
	s_addc_u32 s7, s35, 0
	s_mul_i32 s26, s21, 0x110000
	s_lshl_b32 s27, s25, 1
	s_add_u32 s26, s26, s27
	s_add_u32 s26, s26, 0xbec4000
	s_add_u32 s8, s34, s26
	s_addc_u32 s9, s35, 0
	s_mul_i32 s26, s24, 0x600
	s_mul_i32 s27, s21, 0xc0
	s_add_u32 s26, s26, s27
	s_add_u32 s26, s26, 0xaa44000
	s_add_u32 s10, s34, s26
	s_addc_u32 s11, s35, 0
	s_lshl_b32 s26, s24, 11
	s_lshl_b32 s27, s21, 7
	s_add_u32 s26, s26, s27
	s_add_u32 s26, s26, 0x9a44000
	s_add_u32 s22, s34, s26
	s_addc_u32 s23, s35, 0
	global_load_dwordx4 v[0:3], v202, s[10:11]
	global_load_dwordx4 v[4:7], v202, s[10:11] offset:64
	global_load_dwordx4 v[8:11], v202, s[10:11] offset:128
	global_load_dwordx4 v[12:15], v203, s[10:11]
	global_load_dwordx4 v[16:19], v203, s[10:11] offset:64
	global_load_dwordx4 v[20:23], v203, s[10:11] offset:128
	s_add_u32 m0, s19, 0x0
	s_nop 0
	global_load_lds_dwordx4 v176, s[4:5]
	s_add_u32 m0, s19, 0x400
	s_nop 0
	global_load_lds_dwordx4 v177, s[4:5]
	s_add_u32 m0, s18, 0x4000
	s_nop 0
	global_load_lds_dwordx4 v178, s[6:7]
	s_add_u32 m0, s19, 0x6000
	s_nop 0
	global_load_lds_dwordx4 v179, s[8:9]
	s_add_u32 m0, s19, 0x6400
	s_nop 0
	global_load_lds_dwordx4 v180, s[8:9]
	s_add_u32 s4, s4, 0x20000
	s_addc_u32 s5, s5, 0
	s_add_u32 s6, s6, 0x2000
	s_addc_u32 s7, s7, 0
	s_add_u32 s8, s8, 0x100
	s_addc_u32 s9, s9, 0
	s_add_u32 m0, s19, 0xa000
	s_nop 0
	global_load_lds_dwordx4 v176, s[4:5]
	s_add_u32 m0, s19, 0xa400
	s_nop 0
	global_load_lds_dwordx4 v177, s[4:5]
	s_add_u32 m0, s18, 0xe000
	s_nop 0
	global_load_lds_dwordx4 v178, s[6:7]
	s_add_u32 m0, s19, 0x10000
	s_nop 0
	global_load_lds_dwordx4 v179, s[8:9]
	s_add_u32 m0, s19, 0x10400
	s_nop 0
	global_load_lds_dwordx4 v180, s[8:9]
	s_add_u32 s4, s4, 0x20000
	s_addc_u32 s5, s5, 0
	s_add_u32 s6, s6, 0x2000
	s_addc_u32 s7, s7, 0
	s_add_u32 s8, s8, 0x100
	s_addc_u32 s9, s9, 0
	s_mov_b64 s[28:29], -1
	s_mov_b32 s30, 0xff800000
	v_mov_b32_e32 v238, 0
	v_mov_b32_e32 v239, 0
	v_mov_b32_e32 v240, 0
	v_mov_b32_e32 v241, 0
	v_mov_b32_e32 v242, 0
	v_mov_b32_e32 v243, 0
	v_mov_b32_e32 v244, 0
	v_mov_b32_e32 v245, 0
	v_mov_b32_e32 v152, 0
	v_mov_b32_e32 v154, 0
	v_mov_b32_e32 v24, 0
	v_mov_b32_e32 v25, 0
	v_mov_b32_e32 v26, 0
	v_mov_b32_e32 v27, 0
	v_mov_b32_e32 v28, 0
	v_mov_b32_e32 v29, 0
	v_mov_b32_e32 v30, 0
	v_mov_b32_e32 v31, 0
	v_mov_b32_e32 v32, 0
	v_mov_b32_e32 v33, 0
	v_mov_b32_e32 v34, 0
	v_mov_b32_e32 v35, 0
	v_mov_b32_e32 v36, 0
	v_mov_b32_e32 v37, 0
	v_mov_b32_e32 v38, 0
	v_mov_b32_e32 v39, 0
	v_mov_b32_e32 v153, 0
	v_mov_b32_e32 v155, 0
	v_mov_b32_e32 v40, 0
	v_mov_b32_e32 v41, 0
	v_mov_b32_e32 v42, 0
	v_mov_b32_e32 v43, 0
	v_mov_b32_e32 v44, 0
	v_mov_b32_e32 v45, 0
	v_mov_b32_e32 v46, 0
	v_mov_b32_e32 v47, 0
	v_mov_b32_e32 v48, 0
	v_mov_b32_e32 v49, 0
	v_mov_b32_e32 v50, 0
	v_mov_b32_e32 v51, 0
	v_mov_b32_e32 v52, 0
	v_mov_b32_e32 v53, 0
	v_mov_b32_e32 v54, 0
	v_mov_b32_e32 v55, 0
	s_mov_b32 s17, 0
	s_waitcnt vmcnt(5)
	s_barrier
.Lat_k:
	s_add_u32 m0, s19, 0x14000
	s_nop 0
	global_load_lds_dwordx4 v176, s[4:5]
	s_add_u32 m0, s19, 0x14400
	s_nop 0
	global_load_lds_dwordx4 v177, s[4:5]
	s_add_u32 m0, s18, 0x18000
	s_nop 0
	global_load_lds_dwordx4 v178, s[6:7]
	s_add_u32 m0, s19, 0x1a000
	s_nop 0
	global_load_lds_dwordx4 v179, s[8:9]
	s_add_u32 m0, s19, 0x1a400
	s_nop 0
	global_load_lds_dwordx4 v180, s[8:9]
	s_add_u32 s4, s4, 0x20000
	s_addc_u32 s5, s5, 0
	s_add_u32 s6, s6, 0x2000
	s_addc_u32 s7, s7, 0
	s_add_u32 s8, s8, 0x100
	s_addc_u32 s9, s9, 0
	ds_read_b128 v[88:91], v181
	ds_read_b128 v[92:95], v182
	ds_read_b128 v[96:99], v183
	ds_read_b128 v[100:103], v181 offset:2048
	ds_read_b128 v[104:107], v182 offset:2048
	ds_read_b128 v[108:111], v183 offset:1024
	ds_read_b128 v[112:115], v181 offset:4096
	ds_read_b128 v[116:119], v182 offset:4096
	ds_read_b128 v[120:123], v183 offset:2048
	ds_read_b128 v[124:127], v181 offset:6144
	ds_read_b128 v[128:131], v182 offset:6144
	ds_read_b128 v[132:135], v183 offset:3072
	s_waitcnt lgkmcnt(11)
	v_mfma_f32_16x16x32_bf16 v[56:59], v[88:91], v[0:3], v[238:241]
	v_mfma_f32_16x16x32_bf16 v[72:75], v[88:91], v[12:15], v[242:245]
	s_waitcnt lgkmcnt(10)
	v_mfma_f32_16x16x32_bf16 v[56:59], v[92:95], v[4:7], v[56:59]
	v_mfma_f32_16x16x32_bf16 v[72:75], v[92:95], v[16:19], v[72:75]
	s_waitcnt lgkmcnt(9)
	v_mfma_f32_16x16x32_bf16 v[56:59], v[96:99], v[8:11], v[56:59]
	v_mfma_f32_16x16x32_bf16 v[72:75], v[96:99], v[20:23], v[72:75]
	s_waitcnt lgkmcnt(8)
	v_mfma_f32_16x16x32_bf16 v[60:63], v[100:103], v[0:3], v[238:241]
	v_mfma_f32_16x16x32_bf16 v[76:79], v[100:103], v[12:15], v[242:245]
	s_waitcnt lgkmcnt(7)
	v_mfma_f32_16x16x32_bf16 v[60:63], v[104:107], v[4:7], v[60:63]
	v_mfma_f32_16x16x32_bf16 v[76:79], v[104:107], v[16:19], v[76:79]
	s_waitcnt lgkmcnt(6)
	v_mfma_f32_16x16x32_bf16 v[60:63], v[108:111], v[8:11], v[60:63]
	v_mfma_f32_16x16x32_bf16 v[76:79], v[108:111], v[20:23], v[76:79]
	s_waitcnt lgkmcnt(5)
	v_mfma_f32_16x16x32_bf16 v[64:67], v[112:115], v[0:3], v[238:241]
	v_mfma_f32_16x16x32_bf16 v[80:83], v[112:115], v[12:15], v[242:245]
	s_waitcnt lgkmcnt(4)
	v_mfma_f32_16x16x32_bf16 v[64:67], v[116:119], v[4:7], v[64:67]
	v_mfma_f32_16x16x32_bf16 v[80:83], v[116:119], v[16:19], v[80:83]
	s_waitcnt lgkmcnt(3)
	v_mfma_f32_16x16x32_bf16 v[64:67], v[120:123], v[8:11], v[64:67]
	v_mfma_f32_16x16x32_bf16 v[80:83], v[120:123], v[20:23], v[80:83]
	s_waitcnt lgkmcnt(2)
	v_mfma_f32_16x16x32_bf16 v[68:71], v[124:127], v[0:3], v[238:241]
	v_mfma_f32_16x16x32_bf16 v[84:87], v[124:127], v[12:15], v[242:245]
	s_waitcnt lgkmcnt(1)
	v_mfma_f32_16x16x32_bf16 v[68:71], v[128:131], v[4:7], v[68:71]
	v_mfma_f32_16x16x32_bf16 v[84:87], v[128:131], v[16:19], v[84:87]
	s_waitcnt lgkmcnt(0)
	v_mfma_f32_16x16x32_bf16 v[68:71], v[132:135], v[8:11], v[68:71]
	v_mfma_f32_16x16x32_bf16 v[84:87], v[132:135], v[20:23], v[84:87]
	ds_read_b64 v[206:207], v184
	ds_read_b64 v[208:209], v185
	ds_read_b64 v[210:211], v186
	ds_read_b64 v[212:213], v187
	ds_read_b64 v[214:215], v184 offset:4096
	ds_read_b64 v[216:217], v185 offset:4096
	ds_read_b64 v[218:219], v186 offset:4096
	ds_read_b64 v[220:221], v187 offset:4096
	ds_read_b64 v[222:223], v184 offset:8192
	ds_read_b64 v[224:225], v185 offset:8192
	ds_read_b64 v[226:227], v186 offset:8192
	ds_read_b64 v[228:229], v187 offset:8192
	ds_read_b64 v[230:231], v184 offset:12288
	ds_read_b64 v[232:233], v185 offset:12288
	ds_read_b64 v[234:235], v186 offset:12288
	ds_read_b64 v[236:237], v187 offset:12288
	s_nop 7
	v_max_f32_e32 v156, v56, v57
	v_max3_f32 v156, v156, v58, v59
	v_max3_f32 v156, v156, v60, v61
	v_max3_f32 v156, v156, v62, v63
	v_max3_f32 v156, v156, v64, v65
	v_max3_f32 v156, v156, v66, v67
	v_max3_f32 v156, v156, v68, v69
	v_max3_f32 v156, v156, v70, v71
	v_mov_b32_e32 v157, v156
	s_nop 1
	v_permlane16_swap_b32_e32 v156, v157
	v_max_f32_e32 v156, v156, v157
	v_mov_b32_e32 v157, v156
	s_nop 1
	v_permlane32_swap_b32_e32 v156, v157
	v_max_f32_e32 v156, v156, v157
	v_cmp_lt_f32_e32 vcc, 0x41000000, v156
	s_or_b64 vcc, vcc, s[28:29]
	s_cbranch_vccz .Lat_fast_00
	v_max_f32_e32 v156, s30, v156
	v_sub_f32_e32 v158, 0, v156
	v_exp_f32_e32 v158, v158
	v_add_f32_e32 v152, v152, v156
	v_sub_f32_e32 v238, v238, v156
	v_mov_b32_e32 v239, v238
	v_mov_b32_e32 v240, v238
	v_mov_b32_e32 v241, v238
	v_sub_f32_e32 v56, v56, v156
	v_sub_f32_e32 v57, v57, v156
	v_sub_f32_e32 v58, v58, v156
	v_sub_f32_e32 v59, v59, v156
	v_sub_f32_e32 v60, v60, v156
	v_sub_f32_e32 v61, v61, v156
	v_sub_f32_e32 v62, v62, v156
	v_sub_f32_e32 v63, v63, v156
	v_sub_f32_e32 v64, v64, v156
	v_sub_f32_e32 v65, v65, v156
	v_sub_f32_e32 v66, v66, v156
	v_sub_f32_e32 v67, v67, v156
	v_sub_f32_e32 v68, v68, v156
	v_sub_f32_e32 v69, v69, v156
	v_sub_f32_e32 v70, v70, v156
	v_sub_f32_e32 v71, v71, v156
	v_mul_f32_e32 v154, v154, v158
	v_mul_f32_e32 v24, v24, v158
	v_mul_f32_e32 v25, v25, v158
	v_mul_f32_e32 v26, v26, v158
	v_mul_f32_e32 v27, v27, v158
	v_mul_f32_e32 v28, v28, v158
	v_mul_f32_e32 v29, v29, v158
	v_mul_f32_e32 v30, v30, v158
	v_mul_f32_e32 v31, v31, v158
	v_mul_f32_e32 v32, v32, v158
	v_mul_f32_e32 v33, v33, v158
	v_mul_f32_e32 v34, v34, v158
	v_mul_f32_e32 v35, v35, v158
	v_mul_f32_e32 v36, v36, v158
	v_mul_f32_e32 v37, v37, v158
	v_mul_f32_e32 v38, v38, v158
	v_mul_f32_e32 v39, v39, v158
.Lat_fast_00:
	v_exp_f32_e32 v56, v56
	v_exp_f32_e32 v57, v57
	v_exp_f32_e32 v58, v58
	v_exp_f32_e32 v59, v59
	v_exp_f32_e32 v60, v60
	v_exp_f32_e32 v61, v61
	v_exp_f32_e32 v62, v62
	v_exp_f32_e32 v63, v63
	v_exp_f32_e32 v64, v64
	v_exp_f32_e32 v65, v65
	v_exp_f32_e32 v66, v66
	v_exp_f32_e32 v67, v67
	v_exp_f32_e32 v68, v68
	v_exp_f32_e32 v69, v69
	v_exp_f32_e32 v70, v70
	v_exp_f32_e32 v71, v71
	v_add_f32_e32 v157, v56, v57
	v_add_f32_e32 v157, v157, v58
	v_add_f32_e32 v157, v157, v59
	v_add_f32_e32 v157, v157, v60
	v_add_f32_e32 v157, v157, v61
	v_add_f32_e32 v157, v157, v62
	v_add_f32_e32 v157, v157, v63
	v_add_f32_e32 v157, v157, v64
	v_add_f32_e32 v157, v157, v65
	v_add_f32_e32 v157, v157, v66
	v_add_f32_e32 v157, v157, v67
	v_add_f32_e32 v157, v157, v68
	v_add_f32_e32 v157, v157, v69
	v_add_f32_e32 v157, v157, v70
	v_add_f32_e32 v157, v157, v71
	v_add_f32_e32 v154, v154, v157
	v_cvt_pk_bf16_f32 v136, v56, v57
	v_cvt_pk_bf16_f32 v137, v58, v59
	v_cvt_pk_bf16_f32 v138, v60, v61
	v_cvt_pk_bf16_f32 v139, v62, v63
	v_cvt_pk_bf16_f32 v140, v64, v65
	v_cvt_pk_bf16_f32 v141, v66, v67
	v_cvt_pk_bf16_f32 v142, v68, v69
	v_cvt_pk_bf16_f32 v143, v70, v71
	v_max_f32_e32 v164, v72, v73
	v_max3_f32 v164, v164, v74, v75
	v_max3_f32 v164, v164, v76, v77
	v_max3_f32 v164, v164, v78, v79
	v_max3_f32 v164, v164, v80, v81
	v_max3_f32 v164, v164, v82, v83
	v_max3_f32 v164, v164, v84, v85
	v_max3_f32 v164, v164, v86, v87
	v_mov_b32_e32 v165, v164
	s_nop 1
	v_permlane16_swap_b32_e32 v164, v165
	v_max_f32_e32 v164, v164, v165
	v_mov_b32_e32 v165, v164
	s_nop 1
	v_permlane32_swap_b32_e32 v164, v165
	v_max_f32_e32 v164, v164, v165
	v_cmp_lt_f32_e32 vcc, 0x41000000, v164
	s_or_b64 vcc, vcc, s[28:29]
	s_cbranch_vccz .Lat_fast_01
	v_max_f32_e32 v164, s30, v164
	v_sub_f32_e32 v166, 0, v164
	v_exp_f32_e32 v166, v166
	v_add_f32_e32 v153, v153, v164
	v_sub_f32_e32 v242, v242, v164
	v_mov_b32_e32 v243, v242
	v_mov_b32_e32 v244, v242
	v_mov_b32_e32 v245, v242
	v_sub_f32_e32 v72, v72, v164
	v_sub_f32_e32 v73, v73, v164
	v_sub_f32_e32 v74, v74, v164
	v_sub_f32_e32 v75, v75, v164
	v_sub_f32_e32 v76, v76, v164
	v_sub_f32_e32 v77, v77, v164
	v_sub_f32_e32 v78, v78, v164
	v_sub_f32_e32 v79, v79, v164
	v_sub_f32_e32 v80, v80, v164
	v_sub_f32_e32 v81, v81, v164
	v_sub_f32_e32 v82, v82, v164
	v_sub_f32_e32 v83, v83, v164
	v_sub_f32_e32 v84, v84, v164
	v_sub_f32_e32 v85, v85, v164
	v_sub_f32_e32 v86, v86, v164
	v_sub_f32_e32 v87, v87, v164
	v_mul_f32_e32 v155, v155, v166
	v_mul_f32_e32 v40, v40, v166
	v_mul_f32_e32 v41, v41, v166
	v_mul_f32_e32 v42, v42, v166
	v_mul_f32_e32 v43, v43, v166
	v_mul_f32_e32 v44, v44, v166
	v_mul_f32_e32 v45, v45, v166
	v_mul_f32_e32 v46, v46, v166
	v_mul_f32_e32 v47, v47, v166
	v_mul_f32_e32 v48, v48, v166
	v_mul_f32_e32 v49, v49, v166
	v_mul_f32_e32 v50, v50, v166
	v_mul_f32_e32 v51, v51, v166
	v_mul_f32_e32 v52, v52, v166
	v_mul_f32_e32 v53, v53, v166
	v_mul_f32_e32 v54, v54, v166
	v_mul_f32_e32 v55, v55, v166
.Lat_fast_01:
	v_exp_f32_e32 v72, v72
	v_exp_f32_e32 v73, v73
	v_exp_f32_e32 v74, v74
	v_exp_f32_e32 v75, v75
	v_exp_f32_e32 v76, v76
	v_exp_f32_e32 v77, v77
	v_exp_f32_e32 v78, v78
	v_exp_f32_e32 v79, v79
	v_exp_f32_e32 v80, v80
	v_exp_f32_e32 v81, v81
	v_exp_f32_e32 v82, v82
	v_exp_f32_e32 v83, v83
	v_exp_f32_e32 v84, v84
	v_exp_f32_e32 v85, v85
	v_exp_f32_e32 v86, v86
	v_exp_f32_e32 v87, v87
	v_add_f32_e32 v165, v72, v73
	v_add_f32_e32 v165, v165, v74
	v_add_f32_e32 v165, v165, v75
	v_add_f32_e32 v165, v165, v76
	v_add_f32_e32 v165, v165, v77
	v_add_f32_e32 v165, v165, v78
	v_add_f32_e32 v165, v165, v79
	v_add_f32_e32 v165, v165, v80
	v_add_f32_e32 v165, v165, v81
	v_add_f32_e32 v165, v165, v82
	v_add_f32_e32 v165, v165, v83
	v_add_f32_e32 v165, v165, v84
	v_add_f32_e32 v165, v165, v85
	v_add_f32_e32 v165, v165, v86
	v_add_f32_e32 v165, v165, v87
	v_add_f32_e32 v155, v155, v165
	v_cvt_pk_bf16_f32 v144, v72, v73
	v_cvt_pk_bf16_f32 v145, v74, v75
	v_cvt_pk_bf16_f32 v146, v76, v77
	v_cvt_pk_bf16_f32 v147, v78, v79
	v_cvt_pk_bf16_f32 v148, v80, v81
	v_cvt_pk_bf16_f32 v149, v82, v83
	v_cvt_pk_bf16_f32 v150, v84, v85
	v_cvt_pk_bf16_f32 v151, v86, v87
	s_mov_b64 s[28:29], 0
	s_mov_b32 s30, 0
	s_nop 3
	s_waitcnt lgkmcnt(0)
	v_mfma_f32_16x16x32_bf16 v[24:27], v[206:209], v[136:139], v[24:27]
	v_mfma_f32_16x16x32_bf16 v[40:43], v[206:209], v[144:147], v[40:43]
	v_mfma_f32_16x16x32_bf16 v[28:31], v[214:217], v[136:139], v[28:31]
	v_mfma_f32_16x16x32_bf16 v[44:47], v[214:217], v[144:147], v[44:47]
	v_mfma_f32_16x16x32_bf16 v[32:35], v[222:225], v[136:139], v[32:35]
	v_mfma_f32_16x16x32_bf16 v[48:51], v[222:225], v[144:147], v[48:51]
	v_mfma_f32_16x16x32_bf16 v[36:39], v[230:233], v[136:139], v[36:39]
	v_mfma_f32_16x16x32_bf16 v[52:55], v[230:233], v[144:147], v[52:55]
	v_mfma_f32_16x16x32_bf16 v[24:27], v[210:213], v[140:143], v[24:27]
	v_mfma_f32_16x16x32_bf16 v[40:43], v[210:213], v[148:151], v[40:43]
	v_mfma_f32_16x16x32_bf16 v[28:31], v[218:221], v[140:143], v[28:31]
	v_mfma_f32_16x16x32_bf16 v[44:47], v[218:221], v[148:151], v[44:47]
	v_mfma_f32_16x16x32_bf16 v[32:35], v[226:229], v[140:143], v[32:35]
	v_mfma_f32_16x16x32_bf16 v[48:51], v[226:229], v[148:151], v[48:51]
	v_mfma_f32_16x16x32_bf16 v[36:39], v[234:237], v[140:143], v[36:39]
	v_mfma_f32_16x16x32_bf16 v[52:55], v[234:237], v[148:151], v[52:55]
	s_waitcnt vmcnt(5) lgkmcnt(0)
	s_barrier
	s_add_i32 s17, s17, 1
	s_cmp_lt_u32 s17, s16
	s_cbranch_scc0 .Lat_kdone
	s_add_u32 m0, s19, 0x0
	s_nop 0
	global_load_lds_dwordx4 v176, s[4:5]
	s_add_u32 m0, s19, 0x400
	s_nop 0
	global_load_lds_dwordx4 v177, s[4:5]
	s_add_u32 m0, s18, 0x4000
	s_nop 0
	global_load_lds_dwordx4 v178, s[6:7]
	s_add_u32 m0, s19, 0x6000
	s_nop 0
	global_load_lds_dwordx4 v179, s[8:9]
	s_add_u32 m0, s19, 0x6400
	s_nop 0
	global_load_lds_dwordx4 v180, s[8:9]
	s_add_u32 s4, s4, 0x20000
	s_addc_u32 s5, s5, 0
	s_add_u32 s6, s6, 0x2000
	s_addc_u32 s7, s7, 0
	s_add_u32 s8, s8, 0x100
	s_addc_u32 s9, s9, 0
	ds_read_b128 v[88:91], v188
	ds_read_b128 v[92:95], v189
	ds_read_b128 v[96:99], v190
	ds_read_b128 v[100:103], v188 offset:2048
	ds_read_b128 v[104:107], v189 offset:2048
	ds_read_b128 v[108:111], v190 offset:1024
	ds_read_b128 v[112:115], v188 offset:4096
	ds_read_b128 v[116:119], v189 offset:4096
	ds_read_b128 v[120:123], v190 offset:2048
	ds_read_b128 v[124:127], v188 offset:6144
	ds_read_b128 v[128:131], v189 offset:6144
	ds_read_b128 v[132:135], v190 offset:3072
	s_waitcnt lgkmcnt(11)
	v_mfma_f32_16x16x32_bf16 v[56:59], v[88:91], v[0:3], v[238:241]
	v_mfma_f32_16x16x32_bf16 v[72:75], v[88:91], v[12:15], v[242:245]
	s_waitcnt lgkmcnt(10)
	v_mfma_f32_16x16x32_bf16 v[56:59], v[92:95], v[4:7], v[56:59]
	v_mfma_f32_16x16x32_bf16 v[72:75], v[92:95], v[16:19], v[72:75]
	s_waitcnt lgkmcnt(9)
	v_mfma_f32_16x16x32_bf16 v[56:59], v[96:99], v[8:11], v[56:59]
	v_mfma_f32_16x16x32_bf16 v[72:75], v[96:99], v[20:23], v[72:75]
	s_waitcnt lgkmcnt(8)
	v_mfma_f32_16x16x32_bf16 v[60:63], v[100:103], v[0:3], v[238:241]
	v_mfma_f32_16x16x32_bf16 v[76:79], v[100:103], v[12:15], v[242:245]
	s_waitcnt lgkmcnt(7)
	v_mfma_f32_16x16x32_bf16 v[60:63], v[104:107], v[4:7], v[60:63]
	v_mfma_f32_16x16x32_bf16 v[76:79], v[104:107], v[16:19], v[76:79]
	s_waitcnt lgkmcnt(6)
	v_mfma_f32_16x16x32_bf16 v[60:63], v[108:111], v[8:11], v[60:63]
	v_mfma_f32_16x16x32_bf16 v[76:79], v[108:111], v[20:23], v[76:79]
	s_waitcnt lgkmcnt(5)
	v_mfma_f32_16x16x32_bf16 v[64:67], v[112:115], v[0:3], v[238:241]
	v_mfma_f32_16x16x32_bf16 v[80:83], v[112:115], v[12:15], v[242:245]
	s_waitcnt lgkmcnt(4)
	v_mfma_f32_16x16x32_bf16 v[64:67], v[116:119], v[4:7], v[64:67]
	v_mfma_f32_16x16x32_bf16 v[80:83], v[116:119], v[16:19], v[80:83]
	s_waitcnt lgkmcnt(3)
	v_mfma_f32_16x16x32_bf16 v[64:67], v[120:123], v[8:11], v[64:67]
	v_mfma_f32_16x16x32_bf16 v[80:83], v[120:123], v[20:23], v[80:83]
	s_waitcnt lgkmcnt(2)
	v_mfma_f32_16x16x32_bf16 v[68:71], v[124:127], v[0:3], v[238:241]
	v_mfma_f32_16x16x32_bf16 v[84:87], v[124:127], v[12:15], v[242:245]
	s_waitcnt lgkmcnt(1)
	v_mfma_f32_16x16x32_bf16 v[68:71], v[128:131], v[4:7], v[68:71]
	v_mfma_f32_16x16x32_bf16 v[84:87], v[128:131], v[16:19], v[84:87]
	s_waitcnt lgkmcnt(0)
	v_mfma_f32_16x16x32_bf16 v[68:71], v[132:135], v[8:11], v[68:71]
	v_mfma_f32_16x16x32_bf16 v[84:87], v[132:135], v[20:23], v[84:87]
	ds_read_b64 v[206:207], v191
	ds_read_b64 v[208:209], v192
	ds_read_b64 v[210:211], v193
	ds_read_b64 v[212:213], v194
	ds_read_b64 v[214:215], v191 offset:4096
	ds_read_b64 v[216:217], v192 offset:4096
	ds_read_b64 v[218:219], v193 offset:4096
	ds_read_b64 v[220:221], v194 offset:4096
	ds_read_b64 v[222:223], v191 offset:8192
	ds_read_b64 v[224:225], v192 offset:8192
	ds_read_b64 v[226:227], v193 offset:8192
	ds_read_b64 v[228:229], v194 offset:8192
	ds_read_b64 v[230:231], v191 offset:12288
	ds_read_b64 v[232:233], v192 offset:12288
	ds_read_b64 v[234:235], v193 offset:12288
	ds_read_b64 v[236:237], v194 offset:12288
	s_nop 7
	v_max_f32_e32 v156, v56, v57
	v_max3_f32 v156, v156, v58, v59
	v_max3_f32 v156, v156, v60, v61
	v_max3_f32 v156, v156, v62, v63
	v_max3_f32 v156, v156, v64, v65
	v_max3_f32 v156, v156, v66, v67
	v_max3_f32 v156, v156, v68, v69
	v_max3_f32 v156, v156, v70, v71
	v_mov_b32_e32 v157, v156
	s_nop 1
	v_permlane16_swap_b32_e32 v156, v157
	v_max_f32_e32 v156, v156, v157
	v_mov_b32_e32 v157, v156
	s_nop 1
	v_permlane32_swap_b32_e32 v156, v157
	v_max_f32_e32 v156, v156, v157
	v_cmp_lt_f32_e32 vcc, 0x41000000, v156
	s_or_b64 vcc, vcc, s[28:29]
	s_cbranch_vccz .Lat_fast_10
	v_max_f32_e32 v156, s30, v156
	v_sub_f32_e32 v158, 0, v156
	v_exp_f32_e32 v158, v158
	v_add_f32_e32 v152, v152, v156
	v_sub_f32_e32 v238, v238, v156
	v_mov_b32_e32 v239, v238
	v_mov_b32_e32 v240, v238
	v_mov_b32_e32 v241, v238
	v_sub_f32_e32 v56, v56, v156
	v_sub_f32_e32 v57, v57, v156
	v_sub_f32_e32 v58, v58, v156
	v_sub_f32_e32 v59, v59, v156
	v_sub_f32_e32 v60, v60, v156
	v_sub_f32_e32 v61, v61, v156
	v_sub_f32_e32 v62, v62, v156
	v_sub_f32_e32 v63, v63, v156
	v_sub_f32_e32 v64, v64, v156
	v_sub_f32_e32 v65, v65, v156
	v_sub_f32_e32 v66, v66, v156
	v_sub_f32_e32 v67, v67, v156
	v_sub_f32_e32 v68, v68, v156
	v_sub_f32_e32 v69, v69, v156
	v_sub_f32_e32 v70, v70, v156
	v_sub_f32_e32 v71, v71, v156
	v_mul_f32_e32 v154, v154, v158
	v_mul_f32_e32 v24, v24, v158
	v_mul_f32_e32 v25, v25, v158
	v_mul_f32_e32 v26, v26, v158
	v_mul_f32_e32 v27, v27, v158
	v_mul_f32_e32 v28, v28, v158
	v_mul_f32_e32 v29, v29, v158
	v_mul_f32_e32 v30, v30, v158
	v_mul_f32_e32 v31, v31, v158
	v_mul_f32_e32 v32, v32, v158
	v_mul_f32_e32 v33, v33, v158
	v_mul_f32_e32 v34, v34, v158
	v_mul_f32_e32 v35, v35, v158
	v_mul_f32_e32 v36, v36, v158
	v_mul_f32_e32 v37, v37, v158
	v_mul_f32_e32 v38, v38, v158
	v_mul_f32_e32 v39, v39, v158

.Lat_fast_11:
	v_exp_f32_e32 v72, v72
	v_exp_f32_e32 v73, v73
	v_exp_f32_e32 v74, v74
	v_exp_f32_e32 v75, v75
	v_exp_f32_e32 v76, v76
	v_exp_f32_e32 v77, v77
	v_exp_f32_e32 v78, v78
	v_exp_f32_e32 v79, v79
	v_exp_f32_e32 v80, v80
	v_exp_f32_e32 v81, v81
	v_exp_f32_e32 v82, v82
	v_exp_f32_e32 v83, v83
	v_exp_f32_e32 v84, v84
	v_exp_f32_e32 v85, v85
	v_exp_f32_e32 v86, v86
	v_exp_f32_e32 v87, v87
	v_add_f32_e32 v165, v72, v73
	v_add_f32_e32 v165, v165, v74
	v_add_f32_e32 v165, v165, v75
	v_add_f32_e32 v165, v165, v76
	v_add_f32_e32 v165, v165, v77
	v_add_f32_e32 v165, v165, v78
	v_add_f32_e32 v165, v165, v79
	v_add_f32_e32 v165, v165, v80
	v_add_f32_e32 v165, v165, v81
	v_add_f32_e32 v165, v165, v82
	v_add_f32_e32 v165, v165, v83
	v_add_f32_e32 v165, v165, v84
	v_add_f32_e32 v165, v165, v85
	v_add_f32_e32 v165, v165, v86
	v_add_f32_e32 v165, v165, v87
	v_add_f32_e32 v155, v155, v165
	v_cvt_pk_bf16_f32 v144, v72, v73
	v_cvt_pk_bf16_f32 v145, v74, v75
	v_cvt_pk_bf16_f32 v146, v76, v77
	v_cvt_pk_bf16_f32 v147, v78, v79
	v_cvt_pk_bf16_f32 v148, v80, v81
	v_cvt_pk_bf16_f32 v149, v82, v83
	v_cvt_pk_bf16_f32 v150, v84, v85
	v_cvt_pk_bf16_f32 v151, v86, v87
	s_mov_b64 s[28:29], 0
	s_mov_b32 s30, 0
	s_nop 3
	s_waitcnt lgkmcnt(0)
	v_mfma_f32_16x16x32_bf16 v[24:27], v[206:209], v[136:139], v[24:27]
	v_mfma_f32_16x16x32_bf16 v[40:43], v[206:209], v[144:147], v[40:43]
	v_mfma_f32_16x16x32_bf16 v[28:31], v[214:217], v[136:139], v[28:31]
	v_mfma_f32_16x16x32_bf16 v[44:47], v[214:217], v[144:147], v[44:47]
	v_mfma_f32_16x16x32_bf16 v[32:35], v[222:225], v[136:139], v[32:35]
	v_mfma_f32_16x16x32_bf16 v[48:51], v[222:225], v[144:147], v[48:51]
	v_mfma_f32_16x16x32_bf16 v[36:39], v[230:233], v[136:139], v[36:39]
	v_mfma_f32_16x16x32_bf16 v[52:55], v[230:233], v[144:147], v[52:55]
	v_mfma_f32_16x16x32_bf16 v[24:27], v[210:213], v[140:143], v[24:27]
	v_mfma_f32_16x16x32_bf16 v[40:43], v[210:213], v[148:151], v[40:43]
	v_mfma_f32_16x16x32_bf16 v[28:31], v[218:221], v[140:143], v[28:31]
	v_mfma_f32_16x16x32_bf16 v[44:47], v[218:221], v[148:151], v[44:47]
	v_mfma_f32_16x16x32_bf16 v[32:35], v[226:229], v[140:143], v[32:35]
	v_mfma_f32_16x16x32_bf16 v[48:51], v[226:229], v[148:151], v[48:51]
	v_mfma_f32_16x16x32_bf16 v[36:39], v[234:237], v[140:143], v[36:39]
	v_mfma_f32_16x16x32_bf16 v[52:55], v[234:237], v[148:151], v[52:55]
	s_waitcnt vmcnt(5) lgkmcnt(0)
	s_barrier
	s_add_i32 s17, s17, 1
	s_cmp_lt_u32 s17, s16
	s_cbranch_scc0 .Lat_kdone
	s_add_u32 m0, s19, 0xa000
	s_nop 0
	global_load_lds_dwordx4 v176, s[4:5]
	s_add_u32 m0, s19, 0xa400
	s_nop 0
	global_load_lds_dwordx4 v177, s[4:5]
	s_add_u32 m0, s18, 0xe000
	s_nop 0
	global_load_lds_dwordx4 v178, s[6:7]
	s_add_u32 m0, s19, 0x10000
	s_nop 0
	global_load_lds_dwordx4 v179, s[8:9]
	s_add_u32 m0, s19, 0x10400
	s_nop 0
	global_load_lds_dwordx4 v180, s[8:9]
	s_add_u32 s4, s4, 0x20000
	s_addc_u32 s5, s5, 0
	s_add_u32 s6, s6, 0x2000
	s_addc_u32 s7, s7, 0
	s_add_u32 s8, s8, 0x100
	s_addc_u32 s9, s9, 0
	ds_read_b128 v[88:91], v195
	ds_read_b128 v[92:95], v196
	ds_read_b128 v[96:99], v197
	ds_read_b128 v[100:103], v195 offset:2048
	ds_read_b128 v[104:107], v196 offset:2048
	ds_read_b128 v[108:111], v197 offset:1024
	ds_read_b128 v[112:115], v195 offset:4096
	ds_read_b128 v[116:119], v196 offset:4096
	ds_read_b128 v[120:123], v197 offset:2048
	ds_read_b128 v[124:127], v195 offset:6144
	ds_read_b128 v[128:131], v196 offset:6144
	ds_read_b128 v[132:135], v197 offset:3072
	s_waitcnt lgkmcnt(11)
	v_mfma_f32_16x16x32_bf16 v[56:59], v[88:91], v[0:3], v[238:241]
	v_mfma_f32_16x16x32_bf16 v[72:75], v[88:91], v[12:15], v[242:245]
	s_waitcnt lgkmcnt(10)
	v_mfma_f32_16x16x32_bf16 v[56:59], v[92:95], v[4:7], v[56:59]
	v_mfma_f32_16x16x32_bf16 v[72:75], v[92:95], v[16:19], v[72:75]
	s_waitcnt lgkmcnt(9)
	v_mfma_f32_16x16x32_bf16 v[56:59], v[96:99], v[8:11], v[56:59]
	v_mfma_f32_16x16x32_bf16 v[72:75], v[96:99], v[20:23], v[72:75]
	s_waitcnt lgkmcnt(8)
	v_mfma_f32_16x16x32_bf16 v[60:63], v[100:103], v[0:3], v[238:241]
	v_mfma_f32_16x16x32_bf16 v[76:79], v[100:103], v[12:15], v[242:245]
	s_waitcnt lgkmcnt(7)
	v_mfma_f32_16x16x32_bf16 v[60:63], v[104:107], v[4:7], v[60:63]
	v_mfma_f32_16x16x32_bf16 v[76:79], v[104:107], v[16:19], v[76:79]
	s_waitcnt lgkmcnt(6)
	v_mfma_f32_16x16x32_bf16 v[60:63], v[108:111], v[8:11], v[60:63]
	v_mfma_f32_16x16x32_bf16 v[76:79], v[108:111], v[20:23], v[76:79]
	s_waitcnt lgkmcnt(5)
	v_mfma_f32_16x16x32_bf16 v[64:67], v[112:115], v[0:3], v[238:241]
	v_mfma_f32_16x16x32_bf16 v[80:83], v[112:115], v[12:15], v[242:245]
	s_waitcnt lgkmcnt(4)
	v_mfma_f32_16x16x32_bf16 v[64:67], v[116:119], v[4:7], v[64:67]
	v_mfma_f32_16x16x32_bf16 v[80:83], v[116:119], v[16:19], v[80:83]
	s_waitcnt lgkmcnt(3)
	v_mfma_f32_16x16x32_bf16 v[64:67], v[120:123], v[8:11], v[64:67]
	v_mfma_f32_16x16x32_bf16 v[80:83], v[120:123], v[20:23], v[80:83]
	s_waitcnt lgkmcnt(2)
	v_mfma_f32_16x16x32_bf16 v[68:71], v[124:127], v[0:3], v[238:241]
	v_mfma_f32_16x16x32_bf16 v[84:87], v[124:127], v[12:15], v[242:245]
	s_waitcnt lgkmcnt(1)
	v_mfma_f32_16x16x32_bf16 v[68:71], v[128:131], v[4:7], v[68:71]
	v_mfma_f32_16x16x32_bf16 v[84:87], v[128:131], v[16:19], v[84:87]
	s_waitcnt lgkmcnt(0)
	v_mfma_f32_16x16x32_bf16 v[68:71], v[132:135], v[8:11], v[68:71]
	v_mfma_f32_16x16x32_bf16 v[84:87], v[132:135], v[20:23], v[84:87]
	ds_read_b64 v[206:207], v198
	ds_read_b64 v[208:209], v199
	ds_read_b64 v[210:211], v200
	ds_read_b64 v[212:213], v201
	ds_read_b64 v[214:215], v198 offset:4096
	ds_read_b64 v[216:217], v199 offset:4096
	ds_read_b64 v[218:219], v200 offset:4096
	ds_read_b64 v[220:221], v201 offset:4096
	ds_read_b64 v[222:223], v198 offset:8192
	ds_read_b64 v[224:225], v199 offset:8192
	ds_read_b64 v[226:227], v200 offset:8192
	ds_read_b64 v[228:229], v201 offset:8192
	ds_read_b64 v[230:231], v198 offset:12288
	ds_read_b64 v[232:233], v199 offset:12288
	ds_read_b64 v[234:235], v200 offset:12288
	ds_read_b64 v[236:237], v201 offset:12288
	s_nop 7
	v_max_f32_e32 v156, v56, v57
	v_max3_f32 v156, v156, v58, v59
	v_max3_f32 v156, v156, v60, v61
	v_max3_f32 v156, v156, v62, v63
	v_max3_f32 v156, v156, v64, v65
	v_max3_f32 v156, v156, v66, v67
	v_max3_f32 v156, v156, v68, v69
	v_max3_f32 v156, v156, v70, v71
	v_mov_b32_e32 v157, v156
	s_nop 1
	v_permlane16_swap_b32_e32 v156, v157
	v_max_f32_e32 v156, v156, v157
	v_mov_b32_e32 v157, v156
	s_nop 1
	v_permlane32_swap_b32_e32 v156, v157
	v_max_f32_e32 v156, v156, v157
	v_cmp_lt_f32_e32 vcc, 0x41000000, v156
	s_or_b64 vcc, vcc, s[28:29]
	s_cbranch_vccz .Lat_fast_20
	v_max_f32_e32 v156, s30, v156
	v_sub_f32_e32 v158, 0, v156
	v_exp_f32_e32 v158, v158
	v_add_f32_e32 v152, v152, v156
	v_sub_f32_e32 v238, v238, v156
	v_mov_b32_e32 v239, v238
	v_mov_b32_e32 v240, v238
	v_mov_b32_e32 v241, v238
	v_sub_f32_e32 v56, v56, v156
	v_sub_f32_e32 v57, v57, v156
	v_sub_f32_e32 v58, v58, v156
	v_sub_f32_e32 v59, v59, v156
	v_sub_f32_e32 v60, v60, v156
	v_sub_f32_e32 v61, v61, v156
	v_sub_f32_e32 v62, v62, v156
	v_sub_f32_e32 v63, v63, v156
	v_sub_f32_e32 v64, v64, v156
	v_sub_f32_e32 v65, v65, v156
	v_sub_f32_e32 v66, v66, v156
	v_sub_f32_e32 v67, v67, v156
	v_sub_f32_e32 v68, v68, v156
	v_sub_f32_e32 v69, v69, v156
	v_sub_f32_e32 v70, v70, v156
	v_sub_f32_e32 v71, v71, v156
	v_mul_f32_e32 v154, v154, v158
	v_mul_f32_e32 v24, v24, v158
	v_mul_f32_e32 v25, v25, v158
	v_mul_f32_e32 v26, v26, v158
	v_mul_f32_e32 v27, v27, v158
	v_mul_f32_e32 v28, v28, v158
	v_mul_f32_e32 v29, v29, v158
	v_mul_f32_e32 v30, v30, v158
	v_mul_f32_e32 v31, v31, v158
	v_mul_f32_e32 v32, v32, v158
	v_mul_f32_e32 v33, v33, v158
	v_mul_f32_e32 v34, v34, v158
	v_mul_f32_e32 v35, v35, v158
	v_mul_f32_e32 v36, v36, v158
	v_mul_f32_e32 v37, v37, v158
	v_mul_f32_e32 v38, v38, v158
	v_mul_f32_e32 v39, v39, v158

.Lat_fast_21:
	v_exp_f32_e32 v72, v72
	v_exp_f32_e32 v73, v73
	v_exp_f32_e32 v74, v74
	v_exp_f32_e32 v75, v75
	v_exp_f32_e32 v76, v76
	v_exp_f32_e32 v77, v77
	v_exp_f32_e32 v78, v78
	v_exp_f32_e32 v79, v79
	v_exp_f32_e32 v80, v80
	v_exp_f32_e32 v81, v81
	v_exp_f32_e32 v82, v82
	v_exp_f32_e32 v83, v83
	v_exp_f32_e32 v84, v84
	v_exp_f32_e32 v85, v85
	v_exp_f32_e32 v86, v86
	v_exp_f32_e32 v87, v87
	v_add_f32_e32 v165, v72, v73
	v_add_f32_e32 v165, v165, v74
	v_add_f32_e32 v165, v165, v75
	v_add_f32_e32 v165, v165, v76
	v_add_f32_e32 v165, v165, v77
	v_add_f32_e32 v165, v165, v78
	v_add_f32_e32 v165, v165, v79
	v_add_f32_e32 v165, v165, v80
	v_add_f32_e32 v165, v165, v81
	v_add_f32_e32 v165, v165, v82
	v_add_f32_e32 v165, v165, v83
	v_add_f32_e32 v165, v165, v84
	v_add_f32_e32 v165, v165, v85
	v_add_f32_e32 v165, v165, v86
	v_add_f32_e32 v165, v165, v87
	v_add_f32_e32 v155, v155, v165
	v_cvt_pk_bf16_f32 v144, v72, v73
	v_cvt_pk_bf16_f32 v145, v74, v75
	v_cvt_pk_bf16_f32 v146, v76, v77
	v_cvt_pk_bf16_f32 v147, v78, v79
	v_cvt_pk_bf16_f32 v148, v80, v81
	v_cvt_pk_bf16_f32 v149, v82, v83
	v_cvt_pk_bf16_f32 v150, v84, v85
	v_cvt_pk_bf16_f32 v151, v86, v87
	s_mov_b64 s[28:29], 0
	s_mov_b32 s30, 0
	s_nop 3
	s_waitcnt lgkmcnt(0)
	v_mfma_f32_16x16x32_bf16 v[24:27], v[206:209], v[136:139], v[24:27]
	v_mfma_f32_16x16x32_bf16 v[40:43], v[206:209], v[144:147], v[40:43]
	v_mfma_f32_16x16x32_bf16 v[28:31], v[214:217], v[136:139], v[28:31]
	v_mfma_f32_16x16x32_bf16 v[44:47], v[214:217], v[144:147], v[44:47]
	v_mfma_f32_16x16x32_bf16 v[32:35], v[222:225], v[136:139], v[32:35]
	v_mfma_f32_16x16x32_bf16 v[48:51], v[222:225], v[144:147], v[48:51]
	v_mfma_f32_16x16x32_bf16 v[36:39], v[230:233], v[136:139], v[36:39]
	v_mfma_f32_16x16x32_bf16 v[52:55], v[230:233], v[144:147], v[52:55]
	v_mfma_f32_16x16x32_bf16 v[24:27], v[210:213], v[140:143], v[24:27]
	v_mfma_f32_16x16x32_bf16 v[40:43], v[210:213], v[148:151], v[40:43]
	v_mfma_f32_16x16x32_bf16 v[28:31], v[218:221], v[140:143], v[28:31]
	v_mfma_f32_16x16x32_bf16 v[44:47], v[218:221], v[148:151], v[44:47]
	v_mfma_f32_16x16x32_bf16 v[32:35], v[226:229], v[140:143], v[32:35]
	v_mfma_f32_16x16x32_bf16 v[48:51], v[226:229], v[148:151], v[48:51]
	v_mfma_f32_16x16x32_bf16 v[36:39], v[234:237], v[140:143], v[36:39]
	v_mfma_f32_16x16x32_bf16 v[52:55], v[234:237], v[148:151], v[52:55]
	s_waitcnt vmcnt(5) lgkmcnt(0)
	s_barrier
	s_add_i32 s17, s17, 1
	s_cmp_lt_u32 s17, s16
	s_cbranch_scc1 .Lat_k
.Lat_kdone:
	s_waitcnt vmcnt(0)
	s_barrier
	v_mov_b32_e32 v156, v154
	s_nop 1
	v_permlane16_swap_b32_e32 v154, v156
	v_add_f32_e32 v154, v154, v156
	v_mov_b32_e32 v156, v154
	s_nop 1
	v_permlane32_swap_b32_e32 v154, v156
	v_add_f32_e32 v154, v154, v156
	v_mov_b32_e32 v157, v155
	s_nop 1
	v_permlane16_swap_b32_e32 v155, v157
	v_add_f32_e32 v155, v155, v157
	v_mov_b32_e32 v157, v155
	s_nop 1
	v_permlane32_swap_b32_e32 v155, v157
	v_add_f32_e32 v155, v155, v157
	v_and_b32_e32 v173, 63, v204
	s_and_b32 s26, s18, 0xc00
	s_mul_i32 s26, s26, 10
	v_lshlrev_b32_e32 v174, 4, v173
	v_add_u32_e32 v174, s26, v174
	v_lshlrev_b32_e32 v175, 2, v173
	v_add_u32_e32 v175, s26, v175
	v_add_u32_e32 v175, 0x2000, v175
	s_nop 7
	s_nop 7
	s_cmp_eq_u32 s20, 0
	s_cbranch_scc1 .Lat_wait
	ds_write_b128 v174, v[24:27] offset:0
	ds_write_b128 v174, v[28:31] offset:1024
	ds_write_b128 v174, v[32:35] offset:2048
	ds_write_b128 v174, v[36:39] offset:3072
	ds_write_b32 v175, v152 offset:0
	ds_write_b32 v175, v154 offset:512
	ds_write_b128 v174, v[40:43] offset:4096
	ds_write_b128 v174, v[44:47] offset:5120
	ds_write_b128 v174, v[48:51] offset:6144
	ds_write_b128 v174, v[52:55] offset:7168
	ds_write_b32 v175, v153 offset:256
	ds_write_b32 v175, v155 offset:768
.Lat_wait:
	s_waitcnt lgkmcnt(0)
	s_barrier
	s_cmp_eq_u32 s20, 0
	s_cbranch_scc0 .Lat_done
	ds_read_b32 v158, v175 offset:0
	ds_read_b32 v159, v175 offset:512
	ds_read_b128 v[88:91], v174 offset:0
	ds_read_b128 v[100:103], v174 offset:1024
	ds_read_b128 v[112:115], v174 offset:2048
	ds_read_b128 v[124:127], v174 offset:3072
	s_waitcnt lgkmcnt(0)
	v_max_f32_e32 v160, v152, v158
	v_sub_f32_e32 v161, v152, v160
	v_exp_f32_e32 v161, v161
	v_sub_f32_e32 v162, v158, v160
	v_exp_f32_e32 v162, v162
	v_mul_f32_e32 v163, v154, v161
	v_fma_f32 v163, v159, v162, v163
	v_rcp_f32_e32 v163, v163
	s_nop 0
	v_mul_f32_e32 v161, v161, v163
	v_mul_f32_e32 v162, v162, v163
	v_mul_f32_e32 v24, v24, v161
	v_fma_f32 v24, v88, v162, v24
	v_mul_f32_e32 v25, v25, v161
	v_fma_f32 v25, v89, v162, v25
	v_mul_f32_e32 v26, v26, v161
	v_fma_f32 v26, v90, v162, v26
	v_mul_f32_e32 v27, v27, v161
	v_fma_f32 v27, v91, v162, v27
	v_cvt_pk_bf16_f32 v164, v24, v25
	v_cvt_pk_bf16_f32 v165, v26, v27
	global_store_dwordx2 v246, v[164:165], s[22:23] offset:0
	v_mul_f32_e32 v28, v28, v161
	v_fma_f32 v28, v100, v162, v28
	v_mul_f32_e32 v29, v29, v161
	v_fma_f32 v29, v101, v162, v29
	v_mul_f32_e32 v30, v30, v161
	v_fma_f32 v30, v102, v162, v30
	v_mul_f32_e32 v31, v31, v161
	v_fma_f32 v31, v103, v162, v31
	v_cvt_pk_bf16_f32 v166, v28, v29
	v_cvt_pk_bf16_f32 v167, v30, v31
	global_store_dwordx2 v246, v[166:167], s[22:23] offset:32
	v_mul_f32_e32 v32, v32, v161
	v_fma_f32 v32, v112, v162, v32
	v_mul_f32_e32 v33, v33, v161
	v_fma_f32 v33, v113, v162, v33
	v_mul_f32_e32 v34, v34, v161
	v_fma_f32 v34, v114, v162, v34
	v_mul_f32_e32 v35, v35, v161
	v_fma_f32 v35, v115, v162, v35
	v_cvt_pk_bf16_f32 v168, v32, v33
	v_cvt_pk_bf16_f32 v169, v34, v35
	global_store_dwordx2 v246, v[168:169], s[22:23] offset:64
	v_mul_f32_e32 v36, v36, v161
	v_fma_f32 v36, v124, v162, v36
	v_mul_f32_e32 v37, v37, v161
	v_fma_f32 v37, v125, v162, v37
	v_mul_f32_e32 v38, v38, v161
	v_fma_f32 v38, v126, v162, v38
	v_mul_f32_e32 v39, v39, v161
	v_fma_f32 v39, v127, v162, v39
	v_cvt_pk_bf16_f32 v170, v36, v37
	v_cvt_pk_bf16_f32 v171, v38, v39
	global_store_dwordx2 v246, v[170:171], s[22:23] offset:96
	s_add_u32 s22, s22, 0x8000
	s_addc_u32 s23, s23, 0
	ds_read_b32 v158, v175 offset:256
	ds_read_b32 v159, v175 offset:768
	ds_read_b128 v[88:91], v174 offset:4096
	ds_read_b128 v[100:103], v174 offset:5120
	ds_read_b128 v[112:115], v174 offset:6144
	ds_read_b128 v[124:127], v174 offset:7168
	s_waitcnt lgkmcnt(0)
	v_max_f32_e32 v160, v153, v158
	v_sub_f32_e32 v161, v153, v160
	v_exp_f32_e32 v161, v161
	v_sub_f32_e32 v162, v158, v160
	v_exp_f32_e32 v162, v162
	v_mul_f32_e32 v163, v155, v161
	v_fma_f32 v163, v159, v162, v163
	v_rcp_f32_e32 v163, v163
	s_nop 0
	v_mul_f32_e32 v161, v161, v163
	v_mul_f32_e32 v162, v162, v163
	v_mul_f32_e32 v40, v40, v161
	v_fma_f32 v40, v88, v162, v40
	v_mul_f32_e32 v41, v41, v161
	v_fma_f32 v41, v89, v162, v41
	v_mul_f32_e32 v42, v42, v161
	v_fma_f32 v42, v90, v162, v42
	v_mul_f32_e32 v43, v43, v161
	v_fma_f32 v43, v91, v162, v43
	v_cvt_pk_bf16_f32 v164, v40, v41
	v_cvt_pk_bf16_f32 v165, v42, v43
	global_store_dwordx2 v246, v[164:165], s[22:23] offset:0
	v_mul_f32_e32 v44, v44, v161
	v_fma_f32 v44, v100, v162, v44
	v_mul_f32_e32 v45, v45, v161
	v_fma_f32 v45, v101, v162, v45
	v_mul_f32_e32 v46, v46, v161
	v_fma_f32 v46, v102, v162, v46
	v_mul_f32_e32 v47, v47, v161
	v_fma_f32 v47, v103, v162, v47
	v_cvt_pk_bf16_f32 v166, v44, v45
	v_cvt_pk_bf16_f32 v167, v46, v47
	global_store_dwordx2 v246, v[166:167], s[22:23] offset:32
	v_mul_f32_e32 v48, v48, v161
	v_fma_f32 v48, v112, v162, v48
	v_mul_f32_e32 v49, v49, v161
	v_fma_f32 v49, v113, v162, v49
	v_mul_f32_e32 v50, v50, v161
	v_fma_f32 v50, v114, v162, v50
	v_mul_f32_e32 v51, v51, v161
	v_fma_f32 v51, v115, v162, v51
	v_cvt_pk_bf16_f32 v168, v48, v49
	v_cvt_pk_bf16_f32 v169, v50, v51
	global_store_dwordx2 v246, v[168:169], s[22:23] offset:64
	v_mul_f32_e32 v52, v52, v161
	v_fma_f32 v52, v124, v162, v52
	v_mul_f32_e32 v53, v53, v161
	v_fma_f32 v53, v125, v162, v53
	v_mul_f32_e32 v54, v54, v161
	v_fma_f32 v54, v126, v162, v54
	v_mul_f32_e32 v55, v55, v161
	v_fma_f32 v55, v127, v162, v55
	v_cvt_pk_bf16_f32 v170, v52, v53
	v_cvt_pk_bf16_f32 v171, v54, v55
	global_store_dwordx2 v246, v[170:171], s[22:23] offset:96
.Lat_done:
	s_waitcnt lgkmcnt(0)
	s_barrier
	s_add_i32 s14, s14, s15
	s_cmpk_lt_i32 s14, 0x200
	s_cbranch_scc1 .Lat_item
	s_load_dword s6, s[0:1], 0x120

.LBB0_1014:
	s_cmp_lt_i32 s88, 8
	s_cselect_b64 s[4:5], -1, 0
	s_and_b64 s[6:7], s[4:5], s[6:7]
	s_andn2_b64 vcc, exec, s[6:7]
	s_cbranch_vccnz .LBB0_1023
	s_cmpk_gt_i32 s2, 0xff
	s_cbranch_scc1 .LBB0_1023
	s_load_dword s9, s[0:1], 0x120
	v_readfirstlane_b32 s42, v205
	v_and_b32_e32 v192, 15, v204
	v_bfe_u32 v193, v204, 4, 2
	v_lshrrev_b32_e32 v194, 8, v204
	v_bfe_u32 v195, v204, 6, 2
	v_bfe_u32 v196, v204, 1, 3
	v_xor_b32_e32 v197, v193, v196
	v_xor_b32_e32 v198, 4, v197
	v_lshlrev_b32_e32 v197, 4, v197
	v_lshlrev_b32_e32 v198, 4, v198
	v_lshlrev_b32_e32 v199, 14, v194
	v_lshl_add_u32 v199, v192, 7, v199
	v_add_u32_e32 v242, v199, v197
	v_add_u32_e32 v243, v199, v198
	v_lshlrev_b32_e32 v199, 13, v195
	v_lshl_add_u32 v199, v192, 7, v199
	v_add_u32_e32 v199, 0x8000, v199
	v_add_u32_e32 v244, v199, v197
	v_add_u32_e32 v245, v199, v198
	v_add_u32_e32 v246, 0x10000, v242
	v_add_u32_e32 v248, 0x10000, v244
	v_add_u32_e32 v247, 0x10000, v243
	v_add_u32_e32 v249, 0x10000, v245
	v_lshrrev_b32_e32 v199, 3, v204
	v_and_b32_e32 v200, 7, v204
	v_bfe_u32 v201, v204, 4, 3
	v_xor_b32_e32 v200, v200, v201
	v_lshlrev_b32_e32 v200, 4, v200
	v_lshl_add_u32 v238, v199, 11, v200
	v_add_u32_e32 v239, 0x20000, v238
	v_add_u32_e32 v240, 0x40000, v238
	v_add_u32_e32 v241, 0x60000, v238
	s_lshl_b32 s42, s42, 10
	v_and_b32_e32 v202, 0xff, v204
	v_mul_u32_u24_e32 v202, 0x800, v202
	s_mov_b32 s8, s2
	s_and_b32 s44, s8, 7
	s_lshl_b32 s44, s44, 5
	s_lshr_b32 s45, s8, 3
	s_add_i32 s44, s44, s45
	s_lshr_b32 s45, s44, 7
	s_and_b32 s44, s44, 127
	s_and_b32 s98, s44, 3
	s_lshl_b32 s15, s98, 8
	s_lshr_b32 s44, s44, 2
	s_lshl_b32 s14, s44, 8
	s_mul_i32 s44, s14, 0x800
	s_mul_i32 s98, s45, 0x400
	s_add_u32 s44, s44, s98
	s_add_u32 s44, s44, 0x9a44000
	s_add_u32 s10, s34, s44
	s_addc_u32 s11, s35, 0
	s_mul_i32 s44, s15, 0x800
	s_add_u32 s44, s44, s98
	s_add_u32 s44, s44, 0x520000
	s_add_u32 s12, s34, s44
	s_addc_u32 s13, s35, 0
	s_lshl_b32 s45, s45, 16
	s_or_b32 s14, s14, s45
	s_waitcnt vmcnt(0) lgkmcnt(0)
	s_barrier
	s_add_u32 m0, s42, 0x0
	s_nop 0
	global_load_lds_dwordx4 v238, s[10:11]
	s_add_u32 m0, s42, 0x2000
	s_nop 0
	global_load_lds_dwordx4 v239, s[10:11]
	s_add_u32 m0, s42, 0x4000
	s_nop 0
	global_load_lds_dwordx4 v240, s[10:11]
	s_add_u32 m0, s42, 0x6000
	s_nop 0
	global_load_lds_dwordx4 v241, s[10:11]
	s_add_u32 m0, s42, 0x8000
	s_nop 0
	global_load_lds_dwordx4 v238, s[12:13]
	s_add_u32 m0, s42, 0xa000
	s_nop 0
	global_load_lds_dwordx4 v239, s[12:13]
	s_add_u32 m0, s42, 0xc000
	s_nop 0
	global_load_lds_dwordx4 v240, s[12:13]
	s_add_u32 m0, s42, 0xe000
	s_nop 0
	global_load_lds_dwordx4 v241, s[12:13]
	s_waitcnt vmcnt(0)

.Lgl_afterA_outproj:
	s_add_u32 s28, s28, 0x80
	s_addc_u32 s29, s29, 0
	s_add_u32 s30, s30, 0x80
	s_addc_u32 s31, s31, 0
	s_cmp_eq_u32 s33, 3
	s_cselect_b32 s28, s22, s28
	s_cselect_b32 s29, s23, s29
	s_cselect_b32 s30, s24, s30
	s_cselect_b32 s31, s25, s31
	s_setprio 1
	ds_read_b128 v[206:209], v248
	ds_read_b128 v[210:213], v248 offset:2048
	ds_read_b128 v[214:217], v248 offset:4096
	ds_read_b128 v[218:221], v248 offset:6144
	ds_read_b128 v[128:131], v246
	ds_read_b128 v[132:135], v246 offset:2048
	ds_read_b128 v[136:139], v246 offset:4096
	ds_read_b128 v[140:143], v246 offset:6144
	ds_read_b128 v[144:147], v246 offset:8192
	ds_read_b128 v[148:151], v246 offset:10240
	ds_read_b128 v[152:155], v246 offset:12288
	ds_read_b128 v[156:159], v246 offset:14336
	v_mfma_f32_16x16x32_bf16 v[96:99], v[222:225], v[184:187], v[96:99]
	v_mfma_f32_16x16x32_bf16 v[100:103], v[226:229], v[184:187], v[100:103]
	v_mfma_f32_16x16x32_bf16 v[104:107], v[230:233], v[184:187], v[104:107]
	v_mfma_f32_16x16x32_bf16 v[108:111], v[234:237], v[184:187], v[108:111]
	v_mfma_f32_16x16x32_bf16 v[112:115], v[222:225], v[188:191], v[112:115]
	v_mfma_f32_16x16x32_bf16 v[116:119], v[226:229], v[188:191], v[116:119]
	v_mfma_f32_16x16x32_bf16 v[120:123], v[230:233], v[188:191], v[120:123]
	v_mfma_f32_16x16x32_bf16 v[124:127], v[234:237], v[188:191], v[124:127]
	s_waitcnt lgkmcnt(7)
	v_mfma_f32_16x16x32_bf16 v[0:3], v[206:209], v[128:131], v[0:3]
	v_mfma_f32_16x16x32_bf16 v[4:7], v[210:213], v[128:131], v[4:7]
	v_mfma_f32_16x16x32_bf16 v[8:11], v[214:217], v[128:131], v[8:11]
	v_mfma_f32_16x16x32_bf16 v[12:15], v[218:221], v[128:131], v[12:15]
	s_add_u32 m0, s42, 0x0
	s_nop 0
	global_load_lds_dwordx4 v238, s[28:29]
	s_add_u32 m0, s42, 0x2000
	s_nop 0
	global_load_lds_dwordx4 v239, s[28:29]
	ds_read_b128 v[222:225], v249
	ds_read_b128 v[226:229], v249 offset:2048
	s_waitcnt lgkmcnt(8)
	v_mfma_f32_16x16x32_bf16 v[16:19], v[206:209], v[132:135], v[16:19]
	v_mfma_f32_16x16x32_bf16 v[20:23], v[210:213], v[132:135], v[20:23]
	v_mfma_f32_16x16x32_bf16 v[24:27], v[214:217], v[132:135], v[24:27]
	v_mfma_f32_16x16x32_bf16 v[28:31], v[218:221], v[132:135], v[28:31]
	s_add_u32 m0, s42, 0x4000
	s_nop 0
	global_load_lds_dwordx4 v240, s[28:29]
	s_add_u32 m0, s42, 0x6000
	s_nop 0
	global_load_lds_dwordx4 v241, s[28:29]
	ds_read_b128 v[230:233], v249 offset:4096
	ds_read_b128 v[234:237], v249 offset:6144
	s_waitcnt lgkmcnt(9)
	v_mfma_f32_16x16x32_bf16 v[32:35], v[206:209], v[136:139], v[32:35]
	v_mfma_f32_16x16x32_bf16 v[36:39], v[210:213], v[136:139], v[36:39]
	v_mfma_f32_16x16x32_bf16 v[40:43], v[214:217], v[136:139], v[40:43]
	v_mfma_f32_16x16x32_bf16 v[44:47], v[218:221], v[136:139], v[44:47]
	s_add_u32 m0, s42, 0x8000
	s_nop 0
	global_load_lds_dwordx4 v238, s[30:31]
	s_add_u32 m0, s42, 0xa000
	s_nop 0
	global_load_lds_dwordx4 v239, s[30:31]
	ds_read_b128 v[160:163], v247
	ds_read_b128 v[164:167], v247 offset:2048
	s_waitcnt lgkmcnt(10)
	v_mfma_f32_16x16x32_bf16 v[48:51], v[206:209], v[140:143], v[48:51]
	v_mfma_f32_16x16x32_bf16 v[52:55], v[210:213], v[140:143], v[52:55]
	v_mfma_f32_16x16x32_bf16 v[56:59], v[214:217], v[140:143], v[56:59]
	v_mfma_f32_16x16x32_bf16 v[60:63], v[218:221], v[140:143], v[60:63]
	s_add_u32 m0, s42, 0xc000
	s_nop 0
	global_load_lds_dwordx4 v240, s[30:31]
	s_add_u32 m0, s42, 0xe000
	s_nop 0
	global_load_lds_dwordx4 v241, s[30:31]
	ds_read_b128 v[168:171], v247 offset:4096
	ds_read_b128 v[172:175], v247 offset:6144
	s_waitcnt lgkmcnt(11)
	v_mfma_f32_16x16x32_bf16 v[64:67], v[206:209], v[144:147], v[64:67]
	v_mfma_f32_16x16x32_bf16 v[68:71], v[210:213], v[144:147], v[68:71]
	v_mfma_f32_16x16x32_bf16 v[72:75], v[214:217], v[144:147], v[72:75]
	v_mfma_f32_16x16x32_bf16 v[76:79], v[218:221], v[144:147], v[76:79]
	ds_read_b128 v[176:179], v247 offset:8192
	ds_read_b128 v[180:183], v247 offset:10240
	s_waitcnt lgkmcnt(12)
	v_mfma_f32_16x16x32_bf16 v[80:83], v[206:209], v[148:151], v[80:83]
	v_mfma_f32_16x16x32_bf16 v[84:87], v[210:213], v[148:151], v[84:87]
	v_mfma_f32_16x16x32_bf16 v[88:91], v[214:217], v[148:151], v[88:91]
	v_mfma_f32_16x16x32_bf16 v[92:95], v[218:221], v[148:151], v[92:95]
	ds_read_b128 v[184:187], v247 offset:12288
	ds_read_b128 v[188:191], v247 offset:14336
	s_waitcnt lgkmcnt(13)
	v_mfma_f32_16x16x32_bf16 v[96:99], v[206:209], v[152:155], v[96:99]
	v_mfma_f32_16x16x32_bf16 v[100:103], v[210:213], v[152:155], v[100:103]
	v_mfma_f32_16x16x32_bf16 v[104:107], v[214:217], v[152:155], v[104:107]
	v_mfma_f32_16x16x32_bf16 v[108:111], v[218:221], v[152:155], v[108:111]
	s_waitcnt lgkmcnt(12)
	v_mfma_f32_16x16x32_bf16 v[112:115], v[206:209], v[156:159], v[112:115]
	v_mfma_f32_16x16x32_bf16 v[116:119], v[210:213], v[156:159], v[116:119]
	v_mfma_f32_16x16x32_bf16 v[120:123], v[214:217], v[156:159], v[120:123]
	v_mfma_f32_16x16x32_bf16 v[124:127], v[218:221], v[156:159], v[124:127]
	s_waitcnt lgkmcnt(7)
	v_mfma_f32_16x16x32_bf16 v[0:3], v[222:225], v[160:163], v[0:3]
	v_mfma_f32_16x16x32_bf16 v[4:7], v[226:229], v[160:163], v[4:7]
	v_mfma_f32_16x16x32_bf16 v[8:11], v[230:233], v[160:163], v[8:11]
	v_mfma_f32_16x16x32_bf16 v[12:15], v[234:237], v[160:163], v[12:15]
	s_waitcnt lgkmcnt(6)
	v_mfma_f32_16x16x32_bf16 v[16:19], v[222:225], v[164:167], v[16:19]
	v_mfma_f32_16x16x32_bf16 v[20:23], v[226:229], v[164:167], v[20:23]
	v_mfma_f32_16x16x32_bf16 v[24:27], v[230:233], v[164:167], v[24:27]
	v_mfma_f32_16x16x32_bf16 v[28:31], v[234:237], v[164:167], v[28:31]
	s_waitcnt lgkmcnt(5)
	v_mfma_f32_16x16x32_bf16 v[32:35], v[222:225], v[168:171], v[32:35]
	v_mfma_f32_16x16x32_bf16 v[36:39], v[226:229], v[168:171], v[36:39]
	v_mfma_f32_16x16x32_bf16 v[40:43], v[230:233], v[168:171], v[40:43]
	v_mfma_f32_16x16x32_bf16 v[44:47], v[234:237], v[168:171], v[44:47]
	s_waitcnt lgkmcnt(4)
	v_mfma_f32_16x16x32_bf16 v[48:51], v[222:225], v[172:175], v[48:51]
	v_mfma_f32_16x16x32_bf16 v[52:55], v[226:229], v[172:175], v[52:55]
	v_mfma_f32_16x16x32_bf16 v[56:59], v[230:233], v[172:175], v[56:59]
	v_mfma_f32_16x16x32_bf16 v[60:63], v[234:237], v[172:175], v[60:63]
	s_waitcnt lgkmcnt(3)
	v_mfma_f32_16x16x32_bf16 v[64:67], v[222:225], v[176:179], v[64:67]
	v_mfma_f32_16x16x32_bf16 v[68:71], v[226:229], v[176:179], v[68:71]
	v_mfma_f32_16x16x32_bf16 v[72:75], v[230:233], v[176:179], v[72:75]
	v_mfma_f32_16x16x32_bf16 v[76:79], v[234:237], v[176:179], v[76:79]
	s_waitcnt lgkmcnt(2)
	v_mfma_f32_16x16x32_bf16 v[80:83], v[222:225], v[180:183], v[80:83]
	v_mfma_f32_16x16x32_bf16 v[84:87], v[226:229], v[180:183], v[84:87]
	v_mfma_f32_16x16x32_bf16 v[88:91], v[230:233], v[180:183], v[88:91]
	v_mfma_f32_16x16x32_bf16 v[92:95], v[234:237], v[180:183], v[92:95]
	s_setprio 0
	s_waitcnt lgkmcnt(0)
	s_add_u32 s28, s28, 0x80
	s_addc_u32 s29, s29, 0
	s_add_u32 s30, s30, 0x80
	s_addc_u32 s31, s31, 0
	s_add_i32 s33, s33, 1
	s_cmp_lt_u32 s33, 4
	s_cbranch_scc1 .Lgl_ktop_outproj
	v_mfma_f32_16x16x32_bf16 v[96:99], v[222:225], v[184:187], v[96:99]
	v_mfma_f32_16x16x32_bf16 v[100:103], v[226:229], v[184:187], v[100:103]
	v_mfma_f32_16x16x32_bf16 v[104:107], v[230:233], v[184:187], v[104:107]
	v_mfma_f32_16x16x32_bf16 v[108:111], v[234:237], v[184:187], v[108:111]
	v_mfma_f32_16x16x32_bf16 v[112:115], v[222:225], v[188:191], v[112:115]
	v_mfma_f32_16x16x32_bf16 v[116:119], v[226:229], v[188:191], v[116:119]
	v_mfma_f32_16x16x32_bf16 v[120:123], v[230:233], v[188:191], v[120:123]
	v_mfma_f32_16x16x32_bf16 v[124:127], v[234:237], v[188:191], v[124:127]
	s_and_b32 s98, s14, 0xffff
	s_mul_i32 s98, s98, 0x800
	s_lshl_b32 s99, s15, 1
	s_add_u32 s98, s98, s99
	s_lshr_b32 s99, s14, 16
	s_cmp_eq_u32 s99, 0
	s_mov_b32 s99, 0x28c4000
	s_cselect_b32 s99, s99, 0x38c4000
	s_add_u32 s98, s98, s99
	s_add_u32 s100, s34, s98
	s_addc_u32 s101, s35, 0
	v_and_b32_e32 v160, 15, v204
	v_lshrrev_b32_e32 v161, 8, v204
	v_lshl_add_u32 v160, v161, 7, v160
	v_lshlrev_b32_e32 v160, 11, v160
	v_and_b32_e32 v161, 0xc0, v204
	v_lshl_add_u32 v160, v161, 1, v160
	v_bfe_u32 v161, v204, 4, 1
	v_lshl_add_u32 v160, v161, 5, v160
	v_bfe_u32 v161, v204, 5, 1
	v_lshl_add_u32 v160, v161, 4, v160
	s_nop 7
	s_nop 7
	v_cvt_pk_bf16_f32 v0, v0, v1
	v_cvt_pk_bf16_f32 v1, v2, v3
	v_cvt_pk_bf16_f32 v2, v4, v5
	v_cvt_pk_bf16_f32 v3, v6, v7
	v_cvt_pk_bf16_f32 v8, v8, v9
	v_cvt_pk_bf16_f32 v9, v10, v11
	v_cvt_pk_bf16_f32 v10, v12, v13
	v_cvt_pk_bf16_f32 v11, v14, v15
	s_nop 1
	v_permlane16_swap_b32_e32 v0, v2
	v_permlane16_swap_b32_e32 v1, v3
	v_permlane16_swap_b32_e32 v8, v10
	v_permlane16_swap_b32_e32 v9, v11
	global_store_dwordx4 v160, v[0:3], s[100:101] sc1
	global_store_dwordx4 v160, v[8:11], s[100:101] offset:64 sc1
	s_add_u32 s100, s100, 0x8000
	s_addc_u32 s101, s101, 0
	v_cvt_pk_bf16_f32 v16, v16, v17
	v_cvt_pk_bf16_f32 v17, v18, v19
	v_cvt_pk_bf16_f32 v18, v20, v21
	v_cvt_pk_bf16_f32 v19, v22, v23
	v_cvt_pk_bf16_f32 v24, v24, v25
	v_cvt_pk_bf16_f32 v25, v26, v27
	v_cvt_pk_bf16_f32 v26, v28, v29
	v_cvt_pk_bf16_f32 v27, v30, v31
	s_nop 1
	v_permlane16_swap_b32_e32 v16, v18
	v_permlane16_swap_b32_e32 v17, v19
	v_permlane16_swap_b32_e32 v24, v26
	v_permlane16_swap_b32_e32 v25, v27
	global_store_dwordx4 v160, v[16:19], s[100:101] sc1
	global_store_dwordx4 v160, v[24:27], s[100:101] offset:64 sc1
	s_add_u32 s100, s100, 0x8000
	s_addc_u32 s101, s101, 0
	v_cvt_pk_bf16_f32 v32, v32, v33
	v_cvt_pk_bf16_f32 v33, v34, v35
	v_cvt_pk_bf16_f32 v34, v36, v37
	v_cvt_pk_bf16_f32 v35, v38, v39
	v_cvt_pk_bf16_f32 v40, v40, v41
	v_cvt_pk_bf16_f32 v41, v42, v43
	v_cvt_pk_bf16_f32 v42, v44, v45
	v_cvt_pk_bf16_f32 v43, v46, v47
	s_nop 1
	v_permlane16_swap_b32_e32 v32, v34
	v_permlane16_swap_b32_e32 v33, v35
	v_permlane16_swap_b32_e32 v40, v42
	v_permlane16_swap_b32_e32 v41, v43
	global_store_dwordx4 v160, v[32:35], s[100:101] sc1
	global_store_dwordx4 v160, v[40:43], s[100:101] offset:64 sc1
	s_add_u32 s100, s100, 0x8000
	s_addc_u32 s101, s101, 0
	v_cvt_pk_bf16_f32 v48, v48, v49
	v_cvt_pk_bf16_f32 v49, v50, v51
	v_cvt_pk_bf16_f32 v50, v52, v53
	v_cvt_pk_bf16_f32 v51, v54, v55
	v_cvt_pk_bf16_f32 v56, v56, v57
	v_cvt_pk_bf16_f32 v57, v58, v59
	v_cvt_pk_bf16_f32 v58, v60, v61
	v_cvt_pk_bf16_f32 v59, v62, v63
	s_nop 1
	v_permlane16_swap_b32_e32 v48, v50
	v_permlane16_swap_b32_e32 v49, v51
	v_permlane16_swap_b32_e32 v56, v58
	v_permlane16_swap_b32_e32 v57, v59
	global_store_dwordx4 v160, v[48:51], s[100:101] sc1
	global_store_dwordx4 v160, v[56:59], s[100:101] offset:64 sc1
	s_add_u32 s100, s100, 0x8000
	s_addc_u32 s101, s101, 0
	v_cvt_pk_bf16_f32 v64, v64, v65
	v_cvt_pk_bf16_f32 v65, v66, v67
	v_cvt_pk_bf16_f32 v66, v68, v69
	v_cvt_pk_bf16_f32 v67, v70, v71
	v_cvt_pk_bf16_f32 v72, v72, v73
	v_cvt_pk_bf16_f32 v73, v74, v75
	v_cvt_pk_bf16_f32 v74, v76, v77
	v_cvt_pk_bf16_f32 v75, v78, v79
	s_nop 1
	v_permlane16_swap_b32_e32 v64, v66
	v_permlane16_swap_b32_e32 v65, v67
	v_permlane16_swap_b32_e32 v72, v74
	v_permlane16_swap_b32_e32 v73, v75
	global_store_dwordx4 v160, v[64:67], s[100:101] sc1
	global_store_dwordx4 v160, v[72:75], s[100:101] offset:64 sc1
	s_add_u32 s100, s100, 0x8000
	s_addc_u32 s101, s101, 0
	v_cvt_pk_bf16_f32 v80, v80, v81
	v_cvt_pk_bf16_f32 v81, v82, v83
	v_cvt_pk_bf16_f32 v82, v84, v85
	v_cvt_pk_bf16_f32 v83, v86, v87
	v_cvt_pk_bf16_f32 v88, v88, v89
	v_cvt_pk_bf16_f32 v89, v90, v91
	v_cvt_pk_bf16_f32 v90, v92, v93
	v_cvt_pk_bf16_f32 v91, v94, v95
	s_nop 1
	v_permlane16_swap_b32_e32 v80, v82
	v_permlane16_swap_b32_e32 v81, v83
	v_permlane16_swap_b32_e32 v88, v90
	v_permlane16_swap_b32_e32 v89, v91
	global_store_dwordx4 v160, v[80:83], s[100:101] sc1
	global_store_dwordx4 v160, v[88:91], s[100:101] offset:64 sc1
	s_add_u32 s100, s100, 0x8000
	s_addc_u32 s101, s101, 0
	v_cvt_pk_bf16_f32 v96, v96, v97
	v_cvt_pk_bf16_f32 v97, v98, v99
	v_cvt_pk_bf16_f32 v98, v100, v101
	v_cvt_pk_bf16_f32 v99, v102, v103
	v_cvt_pk_bf16_f32 v104, v104, v105
	v_cvt_pk_bf16_f32 v105, v106, v107
	v_cvt_pk_bf16_f32 v106, v108, v109
	v_cvt_pk_bf16_f32 v107, v110, v111
	s_nop 1
	v_permlane16_swap_b32_e32 v96, v98
	v_permlane16_swap_b32_e32 v97, v99
	v_permlane16_swap_b32_e32 v104, v106
	v_permlane16_swap_b32_e32 v105, v107
	global_store_dwordx4 v160, v[96:99], s[100:101] sc1
	global_store_dwordx4 v160, v[104:107], s[100:101] offset:64 sc1
	s_add_u32 s100, s100, 0x8000
	s_addc_u32 s101, s101, 0
	v_cvt_pk_bf16_f32 v112, v112, v113
	v_cvt_pk_bf16_f32 v113, v114, v115
	v_cvt_pk_bf16_f32 v114, v116, v117
	v_cvt_pk_bf16_f32 v115, v118, v119
	v_cvt_pk_bf16_f32 v120, v120, v121
	v_cvt_pk_bf16_f32 v121, v122, v123
	v_cvt_pk_bf16_f32 v122, v124, v125
	v_cvt_pk_bf16_f32 v123, v126, v127
	s_nop 1
	v_permlane16_swap_b32_e32 v112, v114
	v_permlane16_swap_b32_e32 v113, v115
	v_permlane16_swap_b32_e32 v120, v122
	v_permlane16_swap_b32_e32 v121, v123
	global_store_dwordx4 v160, v[112:115], s[100:101] sc1
	global_store_dwordx4 v160, v[120:123], s[100:101] offset:64 sc1
	s_and_b64 vcc, exec, s[26:27]
	s_mov_b32 s14, s20
	s_mov_b32 s15, s21
	s_mov_b64 s[10:11], s[22:23]
	s_mov_b64 s[12:13], s[24:25]
	s_mov_b32 s8, s43
	s_mov_b32 s99, 0
	s_cbranch_vccz .Lgl_tile_outproj
	s_waitcnt vmcnt(0)
	s_barrier
	s_load_dwordx16 s[36:51], s[0:1], 0xc0

.LBB0_1140:
	s_cmp_lt_i32 s88, 10
	s_cselect_b64 s[6:7], -1, 0
	s_and_b64 s[4:5], s[6:7], s[4:5]
	s_andn2_b64 vcc, exec, s[4:5]
	s_cbranch_vccnz .LBB0_1148
	s_cmpk_gt_i32 s2, 0x2bf
	s_cbranch_scc1 .LBB0_1148
	s_load_dword s9, s[0:1], 0x120
	v_readfirstlane_b32 s42, v205
	v_and_b32_e32 v192, 15, v204
	v_bfe_u32 v193, v204, 4, 2
	v_lshrrev_b32_e32 v194, 8, v204
	v_bfe_u32 v195, v204, 6, 2
	v_bfe_u32 v196, v204, 1, 3
	v_xor_b32_e32 v197, v193, v196
	v_xor_b32_e32 v198, 4, v197
	v_lshlrev_b32_e32 v197, 4, v197
	v_lshlrev_b32_e32 v198, 4, v198
	v_lshlrev_b32_e32 v199, 14, v194
	v_lshl_add_u32 v199, v192, 7, v199
	v_add_u32_e32 v242, v199, v197
	v_add_u32_e32 v243, v199, v198
	v_lshlrev_b32_e32 v199, 13, v195
	v_lshl_add_u32 v199, v192, 7, v199
	v_add_u32_e32 v199, 0x8000, v199
	v_add_u32_e32 v244, v199, v197
	v_add_u32_e32 v245, v199, v198
	v_add_u32_e32 v246, 0x10000, v242
	v_add_u32_e32 v248, 0x10000, v244
	v_add_u32_e32 v247, 0x10000, v243
	v_add_u32_e32 v249, 0x10000, v245
	v_lshrrev_b32_e32 v199, 3, v204
	v_and_b32_e32 v200, 7, v204
	v_bfe_u32 v201, v204, 4, 3
	v_xor_b32_e32 v200, v200, v201
	v_lshlrev_b32_e32 v200, 4, v200
	v_lshl_add_u32 v238, v199, 11, v200
	v_add_u32_e32 v239, 0x20000, v238
	v_add_u32_e32 v240, 0x40000, v238
	v_add_u32_e32 v241, 0x60000, v238
	s_lshl_b32 s42, s42, 10
	v_and_b32_e32 v202, 0xff, v204
	v_mul_u32_u24_e32 v202, 0x800, v202
	s_mov_b32 s8, s2
	s_and_b32 s44, s8, 7
	s_mulk_i32 s44, 0x58
	s_lshr_b32 s45, s8, 3
	s_add_i32 s44, s44, s45
	s_cmpk_ge_i32 s44, 176
	s_cselect_b32 s45, 1, 0
	s_cmpk_ge_i32 s44, 352
	s_cselect_b32 s98, 1, 0
	s_add_i32 s45, s45, s98
	s_cmpk_ge_i32 s44, 528
	s_cselect_b32 s98, 1, 0
	s_add_i32 s45, s45, s98
	s_mul_i32 s98, s45, 176
	s_sub_i32 s44, s44, s98
	s_and_b32 s98, s44, 7
	s_lshl_b32 s45, s45, 3
	s_add_i32 s45, s45, s98
	s_lshl_b32 s14, s45, 8
	s_lshr_b32 s44, s44, 3
	s_lshl_b32 s15, s44, 8
	s_mul_i32 s44, s14, 0x800
	s_add_u32 s44, s44, 0x8a44000
	s_add_u32 s10, s34, s44
	s_addc_u32 s11, s35, 0
	s_mul_i32 s44, s15, 0x800
	s_add_u32 s44, s44, 0x7a0000
	s_add_u32 s12, s34, s44
	s_addc_u32 s13, s35, 0
	s_waitcnt vmcnt(0) lgkmcnt(0)
	s_barrier
	s_add_u32 m0, s42, 0x0
	s_nop 0
	global_load_lds_dwordx4 v238, s[10:11]
	s_add_u32 m0, s42, 0x2000
	s_nop 0
	global_load_lds_dwordx4 v239, s[10:11]
	s_add_u32 m0, s42, 0x4000
	s_nop 0
	global_load_lds_dwordx4 v240, s[10:11]
	s_add_u32 m0, s42, 0x6000
	s_nop 0
	global_load_lds_dwordx4 v241, s[10:11]
	s_add_u32 m0, s42, 0x8000
	s_nop 0
	global_load_lds_dwordx4 v238, s[12:13]
	s_add_u32 m0, s42, 0xa000
	s_nop 0
	global_load_lds_dwordx4 v239, s[12:13]
	s_add_u32 m0, s42, 0xc000
	s_nop 0
	global_load_lds_dwordx4 v240, s[12:13]
	s_add_u32 m0, s42, 0xe000
	s_nop 0
	global_load_lds_dwordx4 v241, s[12:13]
	s_waitcnt vmcnt(0)

.Lgl_afterA_ffnup0:
	s_add_u32 s28, s28, 0x80
	s_addc_u32 s29, s29, 0
	s_add_u32 s30, s30, 0x80
	s_addc_u32 s31, s31, 0
	s_cmp_eq_u32 s33, 7
	s_cselect_b32 s28, s22, s28
	s_cselect_b32 s29, s23, s29
	s_cselect_b32 s30, s24, s30
	s_cselect_b32 s31, s25, s31
	s_setprio 1
	ds_read_b128 v[206:209], v248
	ds_read_b128 v[210:213], v248 offset:2048
	ds_read_b128 v[214:217], v248 offset:4096
	ds_read_b128 v[218:221], v248 offset:6144
	ds_read_b128 v[128:131], v246
	ds_read_b128 v[132:135], v246 offset:2048
	ds_read_b128 v[136:139], v246 offset:4096
	ds_read_b128 v[140:143], v246 offset:6144
	ds_read_b128 v[144:147], v246 offset:8192
	ds_read_b128 v[148:151], v246 offset:10240
	ds_read_b128 v[152:155], v246 offset:12288
	ds_read_b128 v[156:159], v246 offset:14336
	v_mfma_f32_16x16x32_bf16 v[96:99], v[222:225], v[184:187], v[96:99]
	v_mfma_f32_16x16x32_bf16 v[100:103], v[226:229], v[184:187], v[100:103]
	v_mfma_f32_16x16x32_bf16 v[104:107], v[230:233], v[184:187], v[104:107]
	v_mfma_f32_16x16x32_bf16 v[108:111], v[234:237], v[184:187], v[108:111]
	v_mfma_f32_16x16x32_bf16 v[112:115], v[222:225], v[188:191], v[112:115]
	v_mfma_f32_16x16x32_bf16 v[116:119], v[226:229], v[188:191], v[116:119]
	v_mfma_f32_16x16x32_bf16 v[120:123], v[230:233], v[188:191], v[120:123]
	v_mfma_f32_16x16x32_bf16 v[124:127], v[234:237], v[188:191], v[124:127]
	s_waitcnt lgkmcnt(7)
	v_mfma_f32_16x16x32_bf16 v[0:3], v[206:209], v[128:131], v[0:3]
	v_mfma_f32_16x16x32_bf16 v[4:7], v[210:213], v[128:131], v[4:7]
	v_mfma_f32_16x16x32_bf16 v[8:11], v[214:217], v[128:131], v[8:11]
	v_mfma_f32_16x16x32_bf16 v[12:15], v[218:221], v[128:131], v[12:15]
	s_add_u32 m0, s42, 0x0
	s_nop 0
	global_load_lds_dwordx4 v238, s[28:29]
	s_add_u32 m0, s42, 0x2000
	s_nop 0
	global_load_lds_dwordx4 v239, s[28:29]
	ds_read_b128 v[222:225], v249
	ds_read_b128 v[226:229], v249 offset:2048
	s_waitcnt lgkmcnt(8)
	v_mfma_f32_16x16x32_bf16 v[16:19], v[206:209], v[132:135], v[16:19]
	v_mfma_f32_16x16x32_bf16 v[20:23], v[210:213], v[132:135], v[20:23]
	v_mfma_f32_16x16x32_bf16 v[24:27], v[214:217], v[132:135], v[24:27]
	v_mfma_f32_16x16x32_bf16 v[28:31], v[218:221], v[132:135], v[28:31]
	s_add_u32 m0, s42, 0x4000
	s_nop 0
	global_load_lds_dwordx4 v240, s[28:29]
	s_add_u32 m0, s42, 0x6000
	s_nop 0
	global_load_lds_dwordx4 v241, s[28:29]
	ds_read_b128 v[230:233], v249 offset:4096
	ds_read_b128 v[234:237], v249 offset:6144
	s_waitcnt lgkmcnt(9)
	v_mfma_f32_16x16x32_bf16 v[32:35], v[206:209], v[136:139], v[32:35]
	v_mfma_f32_16x16x32_bf16 v[36:39], v[210:213], v[136:139], v[36:39]
	v_mfma_f32_16x16x32_bf16 v[40:43], v[214:217], v[136:139], v[40:43]
	v_mfma_f32_16x16x32_bf16 v[44:47], v[218:221], v[136:139], v[44:47]
	s_add_u32 m0, s42, 0x8000
	s_nop 0
	global_load_lds_dwordx4 v238, s[30:31]
	s_add_u32 m0, s42, 0xa000
	s_nop 0
	global_load_lds_dwordx4 v239, s[30:31]
	ds_read_b128 v[160:163], v247
	ds_read_b128 v[164:167], v247 offset:2048
	s_waitcnt lgkmcnt(10)
	v_mfma_f32_16x16x32_bf16 v[48:51], v[206:209], v[140:143], v[48:51]
	v_mfma_f32_16x16x32_bf16 v[52:55], v[210:213], v[140:143], v[52:55]
	v_mfma_f32_16x16x32_bf16 v[56:59], v[214:217], v[140:143], v[56:59]
	v_mfma_f32_16x16x32_bf16 v[60:63], v[218:221], v[140:143], v[60:63]
	s_add_u32 m0, s42, 0xc000
	s_nop 0
	global_load_lds_dwordx4 v240, s[30:31]
	s_add_u32 m0, s42, 0xe000
	s_nop 0
	global_load_lds_dwordx4 v241, s[30:31]
	ds_read_b128 v[168:171], v247 offset:4096
	ds_read_b128 v[172:175], v247 offset:6144
	s_waitcnt lgkmcnt(11)
	v_mfma_f32_16x16x32_bf16 v[64:67], v[206:209], v[144:147], v[64:67]
	v_mfma_f32_16x16x32_bf16 v[68:71], v[210:213], v[144:147], v[68:71]
	v_mfma_f32_16x16x32_bf16 v[72:75], v[214:217], v[144:147], v[72:75]
	v_mfma_f32_16x16x32_bf16 v[76:79], v[218:221], v[144:147], v[76:79]
	ds_read_b128 v[176:179], v247 offset:8192
	ds_read_b128 v[180:183], v247 offset:10240
	s_waitcnt lgkmcnt(12)
	v_mfma_f32_16x16x32_bf16 v[80:83], v[206:209], v[148:151], v[80:83]
	v_mfma_f32_16x16x32_bf16 v[84:87], v[210:213], v[148:151], v[84:87]
	v_mfma_f32_16x16x32_bf16 v[88:91], v[214:217], v[148:151], v[88:91]
	v_mfma_f32_16x16x32_bf16 v[92:95], v[218:221], v[148:151], v[92:95]
	ds_read_b128 v[184:187], v247 offset:12288
	ds_read_b128 v[188:191], v247 offset:14336
	s_waitcnt lgkmcnt(13)
	v_mfma_f32_16x16x32_bf16 v[96:99], v[206:209], v[152:155], v[96:99]
	v_mfma_f32_16x16x32_bf16 v[100:103], v[210:213], v[152:155], v[100:103]
	v_mfma_f32_16x16x32_bf16 v[104:107], v[214:217], v[152:155], v[104:107]
	v_mfma_f32_16x16x32_bf16 v[108:111], v[218:221], v[152:155], v[108:111]
	s_waitcnt lgkmcnt(12)
	v_mfma_f32_16x16x32_bf16 v[112:115], v[206:209], v[156:159], v[112:115]
	v_mfma_f32_16x16x32_bf16 v[116:119], v[210:213], v[156:159], v[116:119]
	v_mfma_f32_16x16x32_bf16 v[120:123], v[214:217], v[156:159], v[120:123]
	v_mfma_f32_16x16x32_bf16 v[124:127], v[218:221], v[156:159], v[124:127]
	s_waitcnt lgkmcnt(7)
	v_mfma_f32_16x16x32_bf16 v[0:3], v[222:225], v[160:163], v[0:3]
	v_mfma_f32_16x16x32_bf16 v[4:7], v[226:229], v[160:163], v[4:7]
	v_mfma_f32_16x16x32_bf16 v[8:11], v[230:233], v[160:163], v[8:11]
	v_mfma_f32_16x16x32_bf16 v[12:15], v[234:237], v[160:163], v[12:15]
	s_waitcnt lgkmcnt(6)
	v_mfma_f32_16x16x32_bf16 v[16:19], v[222:225], v[164:167], v[16:19]
	v_mfma_f32_16x16x32_bf16 v[20:23], v[226:229], v[164:167], v[20:23]
	v_mfma_f32_16x16x32_bf16 v[24:27], v[230:233], v[164:167], v[24:27]
	v_mfma_f32_16x16x32_bf16 v[28:31], v[234:237], v[164:167], v[28:31]
	s_waitcnt lgkmcnt(5)
	v_mfma_f32_16x16x32_bf16 v[32:35], v[222:225], v[168:171], v[32:35]
	v_mfma_f32_16x16x32_bf16 v[36:39], v[226:229], v[168:171], v[36:39]
	v_mfma_f32_16x16x32_bf16 v[40:43], v[230:233], v[168:171], v[40:43]
	v_mfma_f32_16x16x32_bf16 v[44:47], v[234:237], v[168:171], v[44:47]
	s_waitcnt lgkmcnt(4)
	v_mfma_f32_16x16x32_bf16 v[48:51], v[222:225], v[172:175], v[48:51]
	v_mfma_f32_16x16x32_bf16 v[52:55], v[226:229], v[172:175], v[52:55]
	v_mfma_f32_16x16x32_bf16 v[56:59], v[230:233], v[172:175], v[56:59]
	v_mfma_f32_16x16x32_bf16 v[60:63], v[234:237], v[172:175], v[60:63]
	s_waitcnt lgkmcnt(3)
	v_mfma_f32_16x16x32_bf16 v[64:67], v[222:225], v[176:179], v[64:67]
	v_mfma_f32_16x16x32_bf16 v[68:71], v[226:229], v[176:179], v[68:71]
	v_mfma_f32_16x16x32_bf16 v[72:75], v[230:233], v[176:179], v[72:75]
	v_mfma_f32_16x16x32_bf16 v[76:79], v[234:237], v[176:179], v[76:79]
	s_waitcnt lgkmcnt(2)
	v_mfma_f32_16x16x32_bf16 v[80:83], v[222:225], v[180:183], v[80:83]
	v_mfma_f32_16x16x32_bf16 v[84:87], v[226:229], v[180:183], v[84:87]
	v_mfma_f32_16x16x32_bf16 v[88:91], v[230:233], v[180:183], v[88:91]
	v_mfma_f32_16x16x32_bf16 v[92:95], v[234:237], v[180:183], v[92:95]
	s_setprio 0
	s_waitcnt lgkmcnt(0)
	s_add_u32 s28, s28, 0x80
	s_addc_u32 s29, s29, 0
	s_add_u32 s30, s30, 0x80
	s_addc_u32 s31, s31, 0
	s_add_i32 s33, s33, 1
	s_cmp_lt_u32 s33, 8
	s_cbranch_scc1 .Lgl_ktop_ffnup0
	v_mfma_f32_16x16x32_bf16 v[96:99], v[222:225], v[184:187], v[96:99]
	v_mfma_f32_16x16x32_bf16 v[100:103], v[226:229], v[184:187], v[100:103]
	v_mfma_f32_16x16x32_bf16 v[104:107], v[230:233], v[184:187], v[104:107]
	v_mfma_f32_16x16x32_bf16 v[108:111], v[234:237], v[184:187], v[108:111]
	v_mfma_f32_16x16x32_bf16 v[112:115], v[222:225], v[188:191], v[112:115]
	v_mfma_f32_16x16x32_bf16 v[116:119], v[226:229], v[188:191], v[116:119]
	v_mfma_f32_16x16x32_bf16 v[120:123], v[230:233], v[188:191], v[120:123]
	v_mfma_f32_16x16x32_bf16 v[124:127], v[234:237], v[188:191], v[124:127]
	s_mul_i32 s98, s14, 0x1600
	s_add_u32 s98, s98, s15
	s_add_u32 s98, s98, 0x28c4000
	s_add_u32 s100, s34, s98
	s_addc_u32 s101, s35, 0
	v_and_b32_e32 v168, 15, v204
	v_lshrrev_b32_e32 v169, 8, v204
	v_lshl_add_u32 v168, v169, 7, v168
	v_mul_u32_u24_e32 v168, 0x1600, v168
	v_and_b32_e32 v169, 0xc0, v204
	v_add_u32_e32 v168, v168, v169
	v_bfe_u32 v169, v204, 4, 1
	v_lshl_add_u32 v168, v169, 5, v168
	v_bfe_u32 v169, v204, 5, 1
	v_lshl_add_u32 v168, v169, 4, v168
	s_nop 7
	s_nop 7
	v_mul_f32_e32 v160, 0xbfb8aa3b, v0
	v_mul_f32_e32 v161, 0xbfb8aa3b, v1
	v_mul_f32_e32 v162, 0xbfb8aa3b, v2
	v_mul_f32_e32 v163, 0xbfb8aa3b, v3
	v_mul_f32_e32 v164, 0xbfb8aa3b, v8
	v_mul_f32_e32 v165, 0xbfb8aa3b, v9
	v_mul_f32_e32 v166, 0xbfb8aa3b, v10
	v_mul_f32_e32 v167, 0xbfb8aa3b, v11
	v_exp_f32_e32 v160, v160
	v_exp_f32_e32 v161, v161
	v_exp_f32_e32 v162, v162
	v_exp_f32_e32 v163, v163
	v_exp_f32_e32 v164, v164
	v_exp_f32_e32 v165, v165
	v_exp_f32_e32 v166, v166
	v_exp_f32_e32 v167, v167
	v_add_f32_e32 v160, 1.0, v160
	v_add_f32_e32 v161, 1.0, v161
	v_add_f32_e32 v162, 1.0, v162
	v_add_f32_e32 v163, 1.0, v163
	v_add_f32_e32 v164, 1.0, v164
	v_add_f32_e32 v165, 1.0, v165
	v_add_f32_e32 v166, 1.0, v166
	v_add_f32_e32 v167, 1.0, v167
	v_rcp_f32_e32 v160, v160
	v_rcp_f32_e32 v161, v161
	v_rcp_f32_e32 v162, v162
	v_rcp_f32_e32 v163, v163
	v_rcp_f32_e32 v164, v164
	v_rcp_f32_e32 v165, v165
	v_rcp_f32_e32 v166, v166
	v_rcp_f32_e32 v167, v167
	v_mul_f32_e32 v0, v0, v160
	v_mul_f32_e32 v1, v1, v161
	v_mul_f32_e32 v2, v2, v162
	v_mul_f32_e32 v3, v3, v163
	v_mul_f32_e32 v8, v8, v164
	v_mul_f32_e32 v9, v9, v165
	v_mul_f32_e32 v10, v10, v166
	v_mul_f32_e32 v11, v11, v167
	v_mul_f32_e32 v4, v0, v4
	v_mul_f32_e32 v5, v1, v5
	v_mul_f32_e32 v6, v2, v6
	v_mul_f32_e32 v7, v3, v7
	v_mul_f32_e32 v12, v8, v12
	v_mul_f32_e32 v13, v9, v13
	v_mul_f32_e32 v14, v10, v14
	v_mul_f32_e32 v15, v11, v15
	v_cvt_pk_bf16_f32 v0, v4, v5
	v_cvt_pk_bf16_f32 v1, v6, v7
	v_cvt_pk_bf16_f32 v2, v12, v13
	v_cvt_pk_bf16_f32 v3, v14, v15
	s_nop 1
	v_permlane16_swap_b32_e32 v0, v2
	v_permlane16_swap_b32_e32 v1, v3
	global_store_dwordx4 v168, v[0:3], s[100:101] sc1
	s_add_u32 s100, s100, 0x16000
	s_addc_u32 s101, s101, 0
	v_mul_f32_e32 v160, 0xbfb8aa3b, v16
	v_mul_f32_e32 v161, 0xbfb8aa3b, v17
	v_mul_f32_e32 v162, 0xbfb8aa3b, v18
	v_mul_f32_e32 v163, 0xbfb8aa3b, v19
	v_mul_f32_e32 v164, 0xbfb8aa3b, v24
	v_mul_f32_e32 v165, 0xbfb8aa3b, v25
	v_mul_f32_e32 v166, 0xbfb8aa3b, v26
	v_mul_f32_e32 v167, 0xbfb8aa3b, v27
	v_exp_f32_e32 v160, v160
	v_exp_f32_e32 v161, v161
	v_exp_f32_e32 v162, v162
	v_exp_f32_e32 v163, v163
	v_exp_f32_e32 v164, v164
	v_exp_f32_e32 v165, v165
	v_exp_f32_e32 v166, v166
	v_exp_f32_e32 v167, v167
	v_add_f32_e32 v160, 1.0, v160
	v_add_f32_e32 v161, 1.0, v161
	v_add_f32_e32 v162, 1.0, v162
	v_add_f32_e32 v163, 1.0, v163
	v_add_f32_e32 v164, 1.0, v164
	v_add_f32_e32 v165, 1.0, v165
	v_add_f32_e32 v166, 1.0, v166
	v_add_f32_e32 v167, 1.0, v167
	v_rcp_f32_e32 v160, v160
	v_rcp_f32_e32 v161, v161
	v_rcp_f32_e32 v162, v162
	v_rcp_f32_e32 v163, v163
	v_rcp_f32_e32 v164, v164
	v_rcp_f32_e32 v165, v165
	v_rcp_f32_e32 v166, v166
	v_rcp_f32_e32 v167, v167
	v_mul_f32_e32 v16, v16, v160
	v_mul_f32_e32 v17, v17, v161
	v_mul_f32_e32 v18, v18, v162
	v_mul_f32_e32 v19, v19, v163
	v_mul_f32_e32 v24, v24, v164
	v_mul_f32_e32 v25, v25, v165
	v_mul_f32_e32 v26, v26, v166
	v_mul_f32_e32 v27, v27, v167
	v_mul_f32_e32 v20, v16, v20
	v_mul_f32_e32 v21, v17, v21
	v_mul_f32_e32 v22, v18, v22
	v_mul_f32_e32 v23, v19, v23
	v_mul_f32_e32 v28, v24, v28
	v_mul_f32_e32 v29, v25, v29
	v_mul_f32_e32 v30, v26, v30
	v_mul_f32_e32 v31, v27, v31
	v_cvt_pk_bf16_f32 v16, v20, v21
	v_cvt_pk_bf16_f32 v17, v22, v23
	v_cvt_pk_bf16_f32 v18, v28, v29
	v_cvt_pk_bf16_f32 v19, v30, v31
	s_nop 1
	v_permlane16_swap_b32_e32 v16, v18
	v_permlane16_swap_b32_e32 v17, v19
	global_store_dwordx4 v168, v[16:19], s[100:101] sc1
	s_add_u32 s100, s100, 0x16000
	s_addc_u32 s101, s101, 0
	v_mul_f32_e32 v160, 0xbfb8aa3b, v32
	v_mul_f32_e32 v161, 0xbfb8aa3b, v33
	v_mul_f32_e32 v162, 0xbfb8aa3b, v34
	v_mul_f32_e32 v163, 0xbfb8aa3b, v35
	v_mul_f32_e32 v164, 0xbfb8aa3b, v40
	v_mul_f32_e32 v165, 0xbfb8aa3b, v41
	v_mul_f32_e32 v166, 0xbfb8aa3b, v42
	v_mul_f32_e32 v167, 0xbfb8aa3b, v43
	v_exp_f32_e32 v160, v160
	v_exp_f32_e32 v161, v161
	v_exp_f32_e32 v162, v162
	v_exp_f32_e32 v163, v163
	v_exp_f32_e32 v164, v164
	v_exp_f32_e32 v165, v165
	v_exp_f32_e32 v166, v166
	v_exp_f32_e32 v167, v167
	v_add_f32_e32 v160, 1.0, v160
	v_add_f32_e32 v161, 1.0, v161
	v_add_f32_e32 v162, 1.0, v162
	v_add_f32_e32 v163, 1.0, v163
	v_add_f32_e32 v164, 1.0, v164
	v_add_f32_e32 v165, 1.0, v165
	v_add_f32_e32 v166, 1.0, v166
	v_add_f32_e32 v167, 1.0, v167
	v_rcp_f32_e32 v160, v160
	v_rcp_f32_e32 v161, v161
	v_rcp_f32_e32 v162, v162
	v_rcp_f32_e32 v163, v163
	v_rcp_f32_e32 v164, v164
	v_rcp_f32_e32 v165, v165
	v_rcp_f32_e32 v166, v166
	v_rcp_f32_e32 v167, v167
	v_mul_f32_e32 v32, v32, v160
	v_mul_f32_e32 v33, v33, v161
	v_mul_f32_e32 v34, v34, v162
	v_mul_f32_e32 v35, v35, v163
	v_mul_f32_e32 v40, v40, v164
	v_mul_f32_e32 v41, v41, v165
	v_mul_f32_e32 v42, v42, v166
	v_mul_f32_e32 v43, v43, v167
	v_mul_f32_e32 v36, v32, v36
	v_mul_f32_e32 v37, v33, v37
	v_mul_f32_e32 v38, v34, v38
	v_mul_f32_e32 v39, v35, v39
	v_mul_f32_e32 v44, v40, v44
	v_mul_f32_e32 v45, v41, v45
	v_mul_f32_e32 v46, v42, v46
	v_mul_f32_e32 v47, v43, v47
	v_cvt_pk_bf16_f32 v32, v36, v37
	v_cvt_pk_bf16_f32 v33, v38, v39
	v_cvt_pk_bf16_f32 v34, v44, v45
	v_cvt_pk_bf16_f32 v35, v46, v47
	s_nop 1
	v_permlane16_swap_b32_e32 v32, v34
	v_permlane16_swap_b32_e32 v33, v35
	global_store_dwordx4 v168, v[32:35], s[100:101] sc1
	s_add_u32 s100, s100, 0x16000
	s_addc_u32 s101, s101, 0
	v_mul_f32_e32 v160, 0xbfb8aa3b, v48
	v_mul_f32_e32 v161, 0xbfb8aa3b, v49
	v_mul_f32_e32 v162, 0xbfb8aa3b, v50
	v_mul_f32_e32 v163, 0xbfb8aa3b, v51
	v_mul_f32_e32 v164, 0xbfb8aa3b, v56
	v_mul_f32_e32 v165, 0xbfb8aa3b, v57
	v_mul_f32_e32 v166, 0xbfb8aa3b, v58
	v_mul_f32_e32 v167, 0xbfb8aa3b, v59
	v_exp_f32_e32 v160, v160
	v_exp_f32_e32 v161, v161
	v_exp_f32_e32 v162, v162
	v_exp_f32_e32 v163, v163
	v_exp_f32_e32 v164, v164
	v_exp_f32_e32 v165, v165
	v_exp_f32_e32 v166, v166
	v_exp_f32_e32 v167, v167
	v_add_f32_e32 v160, 1.0, v160
	v_add_f32_e32 v161, 1.0, v161
	v_add_f32_e32 v162, 1.0, v162
	v_add_f32_e32 v163, 1.0, v163
	v_add_f32_e32 v164, 1.0, v164
	v_add_f32_e32 v165, 1.0, v165
	v_add_f32_e32 v166, 1.0, v166
	v_add_f32_e32 v167, 1.0, v167
	v_rcp_f32_e32 v160, v160
	v_rcp_f32_e32 v161, v161
	v_rcp_f32_e32 v162, v162
	v_rcp_f32_e32 v163, v163
	v_rcp_f32_e32 v164, v164
	v_rcp_f32_e32 v165, v165
	v_rcp_f32_e32 v166, v166
	v_rcp_f32_e32 v167, v167
	v_mul_f32_e32 v48, v48, v160
	v_mul_f32_e32 v49, v49, v161
	v_mul_f32_e32 v50, v50, v162
	v_mul_f32_e32 v51, v51, v163
	v_mul_f32_e32 v56, v56, v164
	v_mul_f32_e32 v57, v57, v165
	v_mul_f32_e32 v58, v58, v166
	v_mul_f32_e32 v59, v59, v167
	v_mul_f32_e32 v52, v48, v52
	v_mul_f32_e32 v53, v49, v53
	v_mul_f32_e32 v54, v50, v54
	v_mul_f32_e32 v55, v51, v55
	v_mul_f32_e32 v60, v56, v60
	v_mul_f32_e32 v61, v57, v61
	v_mul_f32_e32 v62, v58, v62
	v_mul_f32_e32 v63, v59, v63
	v_cvt_pk_bf16_f32 v48, v52, v53
	v_cvt_pk_bf16_f32 v49, v54, v55
	v_cvt_pk_bf16_f32 v50, v60, v61
	v_cvt_pk_bf16_f32 v51, v62, v63
	s_nop 1
	v_permlane16_swap_b32_e32 v48, v50
	v_permlane16_swap_b32_e32 v49, v51
	global_store_dwordx4 v168, v[48:51], s[100:101] sc1
	s_add_u32 s100, s100, 0x16000
	s_addc_u32 s101, s101, 0
	v_mul_f32_e32 v160, 0xbfb8aa3b, v64
	v_mul_f32_e32 v161, 0xbfb8aa3b, v65
	v_mul_f32_e32 v162, 0xbfb8aa3b, v66
	v_mul_f32_e32 v163, 0xbfb8aa3b, v67
	v_mul_f32_e32 v164, 0xbfb8aa3b, v72
	v_mul_f32_e32 v165, 0xbfb8aa3b, v73
	v_mul_f32_e32 v166, 0xbfb8aa3b, v74
	v_mul_f32_e32 v167, 0xbfb8aa3b, v75
	v_exp_f32_e32 v160, v160
	v_exp_f32_e32 v161, v161
	v_exp_f32_e32 v162, v162
	v_exp_f32_e32 v163, v163
	v_exp_f32_e32 v164, v164
	v_exp_f32_e32 v165, v165
	v_exp_f32_e32 v166, v166
	v_exp_f32_e32 v167, v167
	v_add_f32_e32 v160, 1.0, v160
	v_add_f32_e32 v161, 1.0, v161
	v_add_f32_e32 v162, 1.0, v162
	v_add_f32_e32 v163, 1.0, v163
	v_add_f32_e32 v164, 1.0, v164
	v_add_f32_e32 v165, 1.0, v165
	v_add_f32_e32 v166, 1.0, v166
	v_add_f32_e32 v167, 1.0, v167
	v_rcp_f32_e32 v160, v160
	v_rcp_f32_e32 v161, v161
	v_rcp_f32_e32 v162, v162
	v_rcp_f32_e32 v163, v163
	v_rcp_f32_e32 v164, v164
	v_rcp_f32_e32 v165, v165
	v_rcp_f32_e32 v166, v166
	v_rcp_f32_e32 v167, v167
	v_mul_f32_e32 v64, v64, v160
	v_mul_f32_e32 v65, v65, v161
	v_mul_f32_e32 v66, v66, v162
	v_mul_f32_e32 v67, v67, v163
	v_mul_f32_e32 v72, v72, v164
	v_mul_f32_e32 v73, v73, v165
	v_mul_f32_e32 v74, v74, v166
	v_mul_f32_e32 v75, v75, v167
	v_mul_f32_e32 v68, v64, v68
	v_mul_f32_e32 v69, v65, v69
	v_mul_f32_e32 v70, v66, v70
	v_mul_f32_e32 v71, v67, v71
	v_mul_f32_e32 v76, v72, v76
	v_mul_f32_e32 v77, v73, v77
	v_mul_f32_e32 v78, v74, v78
	v_mul_f32_e32 v79, v75, v79
	v_cvt_pk_bf16_f32 v64, v68, v69
	v_cvt_pk_bf16_f32 v65, v70, v71
	v_cvt_pk_bf16_f32 v66, v76, v77
	v_cvt_pk_bf16_f32 v67, v78, v79
	s_nop 1
	v_permlane16_swap_b32_e32 v64, v66
	v_permlane16_swap_b32_e32 v65, v67
	global_store_dwordx4 v168, v[64:67], s[100:101] sc1
	s_add_u32 s100, s100, 0x16000
	s_addc_u32 s101, s101, 0
	v_mul_f32_e32 v160, 0xbfb8aa3b, v80
	v_mul_f32_e32 v161, 0xbfb8aa3b, v81
	v_mul_f32_e32 v162, 0xbfb8aa3b, v82
	v_mul_f32_e32 v163, 0xbfb8aa3b, v83
	v_mul_f32_e32 v164, 0xbfb8aa3b, v88
	v_mul_f32_e32 v165, 0xbfb8aa3b, v89
	v_mul_f32_e32 v166, 0xbfb8aa3b, v90
	v_mul_f32_e32 v167, 0xbfb8aa3b, v91
	v_exp_f32_e32 v160, v160
	v_exp_f32_e32 v161, v161
	v_exp_f32_e32 v162, v162
	v_exp_f32_e32 v163, v163
	v_exp_f32_e32 v164, v164
	v_exp_f32_e32 v165, v165
	v_exp_f32_e32 v166, v166
	v_exp_f32_e32 v167, v167
	v_add_f32_e32 v160, 1.0, v160
	v_add_f32_e32 v161, 1.0, v161
	v_add_f32_e32 v162, 1.0, v162
	v_add_f32_e32 v163, 1.0, v163
	v_add_f32_e32 v164, 1.0, v164
	v_add_f32_e32 v165, 1.0, v165
	v_add_f32_e32 v166, 1.0, v166
	v_add_f32_e32 v167, 1.0, v167
	v_rcp_f32_e32 v160, v160
	v_rcp_f32_e32 v161, v161
	v_rcp_f32_e32 v162, v162
	v_rcp_f32_e32 v163, v163
	v_rcp_f32_e32 v164, v164
	v_rcp_f32_e32 v165, v165
	v_rcp_f32_e32 v166, v166
	v_rcp_f32_e32 v167, v167
	v_mul_f32_e32 v80, v80, v160
	v_mul_f32_e32 v81, v81, v161
	v_mul_f32_e32 v82, v82, v162
	v_mul_f32_e32 v83, v83, v163
	v_mul_f32_e32 v88, v88, v164
	v_mul_f32_e32 v89, v89, v165
	v_mul_f32_e32 v90, v90, v166
	v_mul_f32_e32 v91, v91, v167
	v_mul_f32_e32 v84, v80, v84
	v_mul_f32_e32 v85, v81, v85
	v_mul_f32_e32 v86, v82, v86
	v_mul_f32_e32 v87, v83, v87
	v_mul_f32_e32 v92, v88, v92
	v_mul_f32_e32 v93, v89, v93
	v_mul_f32_e32 v94, v90, v94
	v_mul_f32_e32 v95, v91, v95
	v_cvt_pk_bf16_f32 v80, v84, v85
	v_cvt_pk_bf16_f32 v81, v86, v87
	v_cvt_pk_bf16_f32 v82, v92, v93
	v_cvt_pk_bf16_f32 v83, v94, v95
	s_nop 1
	v_permlane16_swap_b32_e32 v80, v82
	v_permlane16_swap_b32_e32 v81, v83
	global_store_dwordx4 v168, v[80:83], s[100:101] sc1
	s_add_u32 s100, s100, 0x16000
	s_addc_u32 s101, s101, 0
	v_mul_f32_e32 v160, 0xbfb8aa3b, v96
	v_mul_f32_e32 v161, 0xbfb8aa3b, v97
	v_mul_f32_e32 v162, 0xbfb8aa3b, v98
	v_mul_f32_e32 v163, 0xbfb8aa3b, v99
	v_mul_f32_e32 v164, 0xbfb8aa3b, v104
	v_mul_f32_e32 v165, 0xbfb8aa3b, v105
	v_mul_f32_e32 v166, 0xbfb8aa3b, v106
	v_mul_f32_e32 v167, 0xbfb8aa3b, v107
	v_exp_f32_e32 v160, v160
	v_exp_f32_e32 v161, v161
	v_exp_f32_e32 v162, v162
	v_exp_f32_e32 v163, v163
	v_exp_f32_e32 v164, v164
	v_exp_f32_e32 v165, v165
	v_exp_f32_e32 v166, v166
	v_exp_f32_e32 v167, v167
	v_add_f32_e32 v160, 1.0, v160
	v_add_f32_e32 v161, 1.0, v161
	v_add_f32_e32 v162, 1.0, v162
	v_add_f32_e32 v163, 1.0, v163
	v_add_f32_e32 v164, 1.0, v164
	v_add_f32_e32 v165, 1.0, v165
	v_add_f32_e32 v166, 1.0, v166
	v_add_f32_e32 v167, 1.0, v167
	v_rcp_f32_e32 v160, v160
	v_rcp_f32_e32 v161, v161
	v_rcp_f32_e32 v162, v162
	v_rcp_f32_e32 v163, v163
	v_rcp_f32_e32 v164, v164
	v_rcp_f32_e32 v165, v165
	v_rcp_f32_e32 v166, v166
	v_rcp_f32_e32 v167, v167
	v_mul_f32_e32 v96, v96, v160
	v_mul_f32_e32 v97, v97, v161
	v_mul_f32_e32 v98, v98, v162
	v_mul_f32_e32 v99, v99, v163
	v_mul_f32_e32 v104, v104, v164
	v_mul_f32_e32 v105, v105, v165
	v_mul_f32_e32 v106, v106, v166
	v_mul_f32_e32 v107, v107, v167
	v_mul_f32_e32 v100, v96, v100
	v_mul_f32_e32 v101, v97, v101
	v_mul_f32_e32 v102, v98, v102
	v_mul_f32_e32 v103, v99, v103
	v_mul_f32_e32 v108, v104, v108
	v_mul_f32_e32 v109, v105, v109
	v_mul_f32_e32 v110, v106, v110
	v_mul_f32_e32 v111, v107, v111
	v_cvt_pk_bf16_f32 v96, v100, v101
	v_cvt_pk_bf16_f32 v97, v102, v103
	v_cvt_pk_bf16_f32 v98, v108, v109
	v_cvt_pk_bf16_f32 v99, v110, v111
	s_nop 1
	v_permlane16_swap_b32_e32 v96, v98
	v_permlane16_swap_b32_e32 v97, v99
	global_store_dwordx4 v168, v[96:99], s[100:101] sc1
	s_add_u32 s100, s100, 0x16000
	s_addc_u32 s101, s101, 0
	v_mul_f32_e32 v160, 0xbfb8aa3b, v112
	v_mul_f32_e32 v161, 0xbfb8aa3b, v113
	v_mul_f32_e32 v162, 0xbfb8aa3b, v114
	v_mul_f32_e32 v163, 0xbfb8aa3b, v115
	v_mul_f32_e32 v164, 0xbfb8aa3b, v120
	v_mul_f32_e32 v165, 0xbfb8aa3b, v121
	v_mul_f32_e32 v166, 0xbfb8aa3b, v122
	v_mul_f32_e32 v167, 0xbfb8aa3b, v123
	v_exp_f32_e32 v160, v160
	v_exp_f32_e32 v161, v161
	v_exp_f32_e32 v162, v162
	v_exp_f32_e32 v163, v163
	v_exp_f32_e32 v164, v164
	v_exp_f32_e32 v165, v165
	v_exp_f32_e32 v166, v166
	v_exp_f32_e32 v167, v167
	v_add_f32_e32 v160, 1.0, v160
	v_add_f32_e32 v161, 1.0, v161
	v_add_f32_e32 v162, 1.0, v162
	v_add_f32_e32 v163, 1.0, v163
	v_add_f32_e32 v164, 1.0, v164
	v_add_f32_e32 v165, 1.0, v165
	v_add_f32_e32 v166, 1.0, v166
	v_add_f32_e32 v167, 1.0, v167
	v_rcp_f32_e32 v160, v160
	v_rcp_f32_e32 v161, v161
	v_rcp_f32_e32 v162, v162
	v_rcp_f32_e32 v163, v163
	v_rcp_f32_e32 v164, v164
	v_rcp_f32_e32 v165, v165
	v_rcp_f32_e32 v166, v166
	v_rcp_f32_e32 v167, v167
	v_mul_f32_e32 v112, v112, v160
	v_mul_f32_e32 v113, v113, v161
	v_mul_f32_e32 v114, v114, v162
	v_mul_f32_e32 v115, v115, v163
	v_mul_f32_e32 v120, v120, v164
	v_mul_f32_e32 v121, v121, v165
	v_mul_f32_e32 v122, v122, v166
	v_mul_f32_e32 v123, v123, v167
	v_mul_f32_e32 v116, v112, v116
	v_mul_f32_e32 v117, v113, v117
	v_mul_f32_e32 v118, v114, v118
	v_mul_f32_e32 v119, v115, v119
	v_mul_f32_e32 v124, v120, v124
	v_mul_f32_e32 v125, v121, v125
	v_mul_f32_e32 v126, v122, v126
	v_mul_f32_e32 v127, v123, v127
	v_cvt_pk_bf16_f32 v112, v116, v117
	v_cvt_pk_bf16_f32 v113, v118, v119
	v_cvt_pk_bf16_f32 v114, v124, v125
	v_cvt_pk_bf16_f32 v115, v126, v127
	s_nop 1
	v_permlane16_swap_b32_e32 v112, v114
	v_permlane16_swap_b32_e32 v113, v115
	global_store_dwordx4 v168, v[112:115], s[100:101] sc1
	s_and_b64 vcc, exec, s[26:27]
	s_mov_b32 s14, s20
	s_mov_b32 s15, s21
	s_mov_b64 s[10:11], s[22:23]
	s_mov_b64 s[12:13], s[24:25]
	s_mov_b32 s8, s43
	s_mov_b32 s99, 0
	s_cbranch_vccz .Lgl_tile_ffnup0
	s_waitcnt vmcnt(0)
	s_barrier

.LBB0_1443:
	s_cmp_lt_i32 s88, 16
	s_cselect_b64 s[6:7], -1, 0
	s_and_b64 s[4:5], s[6:7], s[4:5]
	s_andn2_b64 vcc, exec, s[4:5]
	s_cbranch_vccnz .LBB0_1451
	s_cmpk_gt_i32 s2, 0x2bf
	s_cbranch_scc1 .LBB0_1451
	s_load_dword s9, s[0:1], 0x120
	v_readfirstlane_b32 s42, v205
	v_and_b32_e32 v192, 15, v204
	v_bfe_u32 v193, v204, 4, 2
	v_lshrrev_b32_e32 v194, 8, v204
	v_bfe_u32 v195, v204, 6, 2
	v_bfe_u32 v196, v204, 1, 3
	v_xor_b32_e32 v197, v193, v196
	v_xor_b32_e32 v198, 4, v197
	v_lshlrev_b32_e32 v197, 4, v197
	v_lshlrev_b32_e32 v198, 4, v198
	v_lshlrev_b32_e32 v199, 14, v194
	v_lshl_add_u32 v199, v192, 7, v199
	v_add_u32_e32 v242, v199, v197
	v_add_u32_e32 v243, v199, v198
	v_lshlrev_b32_e32 v199, 13, v195
	v_lshl_add_u32 v199, v192, 7, v199
	v_add_u32_e32 v199, 0x8000, v199
	v_add_u32_e32 v244, v199, v197
	v_add_u32_e32 v245, v199, v198
	v_add_u32_e32 v246, 0x10000, v242
	v_add_u32_e32 v248, 0x10000, v244
	v_add_u32_e32 v247, 0x10000, v243
	v_add_u32_e32 v249, 0x10000, v245
	v_lshrrev_b32_e32 v199, 3, v204
	v_and_b32_e32 v200, 7, v204
	v_bfe_u32 v201, v204, 4, 3
	v_xor_b32_e32 v200, v200, v201
	v_lshlrev_b32_e32 v200, 4, v200
	v_lshl_add_u32 v238, v199, 11, v200
	v_add_u32_e32 v239, 0x20000, v238
	v_add_u32_e32 v240, 0x40000, v238
	v_add_u32_e32 v241, 0x60000, v238
	s_lshl_b32 s42, s42, 10
	v_and_b32_e32 v202, 0xff, v204
	v_mul_u32_u24_e32 v202, 0x800, v202
	s_mov_b32 s8, s2
	s_and_b32 s44, s8, 7
	s_mulk_i32 s44, 0x58
	s_lshr_b32 s45, s8, 3
	s_add_i32 s44, s44, s45
	s_cmpk_ge_i32 s44, 176
	s_cselect_b32 s45, 1, 0
	s_cmpk_ge_i32 s44, 352
	s_cselect_b32 s98, 1, 0
	s_add_i32 s45, s45, s98
	s_cmpk_ge_i32 s44, 528
	s_cselect_b32 s98, 1, 0
	s_add_i32 s45, s45, s98
	s_mul_i32 s98, s45, 176
	s_sub_i32 s44, s44, s98
	s_and_b32 s98, s44, 7
	s_lshl_b32 s45, s45, 3
	s_add_i32 s45, s45, s98
	s_lshl_b32 s14, s45, 8
	s_lshr_b32 s44, s44, 3
	s_lshl_b32 s15, s44, 8
	s_mul_i32 s44, s14, 0x800
	s_add_u32 s44, s44, 0x8a44000
	s_add_u32 s10, s34, s44
	s_addc_u32 s11, s35, 0
	s_mul_i32 s44, s15, 0x800
	s_add_u32 s44, s44, 0x12a0000
	s_add_u32 s12, s34, s44
	s_addc_u32 s13, s35, 0
	s_waitcnt vmcnt(0) lgkmcnt(0)
	s_barrier
	s_add_u32 m0, s42, 0x0
	s_nop 0
	global_load_lds_dwordx4 v238, s[10:11]
	s_add_u32 m0, s42, 0x2000
	s_nop 0
	global_load_lds_dwordx4 v239, s[10:11]
	s_add_u32 m0, s42, 0x4000
	s_nop 0
	global_load_lds_dwordx4 v240, s[10:11]
	s_add_u32 m0, s42, 0x6000
	s_nop 0
	global_load_lds_dwordx4 v241, s[10:11]
	s_add_u32 m0, s42, 0x8000
	s_nop 0
	global_load_lds_dwordx4 v238, s[12:13]
	s_add_u32 m0, s42, 0xa000
	s_nop 0
	global_load_lds_dwordx4 v239, s[12:13]
	s_add_u32 m0, s42, 0xc000
	s_nop 0
	global_load_lds_dwordx4 v240, s[12:13]
	s_add_u32 m0, s42, 0xe000
	s_nop 0
	global_load_lds_dwordx4 v241, s[12:13]
	s_waitcnt vmcnt(0)
